# P10 per-token prologue/epilogue: all of a token's input loads requested together (were three dependent steps; norm weights one load per store)
# baseline (speedup 1.0000x reference)
; __device__ __forceinline__ void phase10(const Args& a, LAS unsigned char* lds, int tid, int wave, int lane, int vcu, int G, int emask, bool probe) {
;     ...
;                 const int brow = R < NP ? 0 : 1 + (int)((R - NP) >> 3);
;                 const float* mrow = mod + (size_t)brow * 6144;
;                 float x1v[16];
; #pragma unroll
;                 for (int q = 0; q < 4; ++q) { const f32x4 t4 = *(const f32x4*)(X1 + R * DM + c0 + 4 * q);
; #pragma unroll
;                     for (int e = 0; e < 4; ++e) x1v[4 * q + e] = t4[e]; }
;                 float ss = 0.f;
; #pragma unroll
;                 for (int e = 0; e < 16; ++e) ss += x1v[e] * x1v[e];
;                 const float rstd = 1.0f / sqrtf(wave_sum(ss) * (1.f / DM) + EPS);
;                 float h2[16], am = 0.f;
; #pragma unroll
;                 for (int e = 0; e < 16; ++e) { const int c = c0 + e; h2[e] = x1v[e] * rstd * a.in[16][c] * (1.f + mrow[4096 + c]) + mrow[3072 + c]; am = fmaxf(am, fabsf(h2[e])); }
; #pragma unroll
;                 for (int o = 1; o < 64; o <<= 1) am = fmaxf(am, __shfl_xor(am, o));
;                 const float inv = am > 0.f ? 127.f / am : 0.f; sh[tk] = am * (1.f / 127.f);
; #pragma unroll
;                 for (int q = 0; q < 4; ++q) { unsigned pk = 0;
; #pragma unroll
;                     for (int e = 0; e < 4; ++e) pk |= ((unsigned)(int)rintf(h2[4 * q + e] * inv) & 0xffu) << (8 * e);
;                     hq[tk][q] = pk; }
;                 const int e0 = SEL_E[R * 128 + 2 * lane], e1 = SEL_E[R * 128 + 2 * lane + 1]; const float g0 = SEL_G[R * 128 + 2 * lane], g1 = SEL_G[R * 128 + 2 * lane + 1];
.LBB0_1673:
	s_lshl_b64 s[34:35], s[10:11], 12
	v_lshl_add_u64 v[0:1], v[72:73], 0, s[34:35]
	s_waitcnt lgkmcnt(10)
	global_load_dwordx4 v[20:23], v[0:1], off
	s_waitcnt lgkmcnt(4)
	global_load_dwordx4 v[24:27], v[0:1], off offset:16
	global_load_dwordx4 v[28:31], v[0:1], off offset:32
	global_load_dwordx4 v[16:19], v[0:1], off offset:48
	v_lshl_add_u64 v[0:1], s[8:9], 2, v[86:87]
	v_add_co_u32_e32 v2, vcc, s46, v0
	v_lshl_add_u64 v[8:9], v[0:1], 0, s[28:29]
	s_nop 0
	v_addc_co_u32_e32 v3, vcc, 0, v1, vcc
	global_load_dwordx4 v[32:35], v[2:3], off
	v_lshl_add_u64 v[2:3], v[0:1], 0, s[26:27]
	global_load_dwordx4 v[36:39], v[2:3], off offset:16
	global_load_dwordx4 v[40:43], v[2:3], off offset:32
	global_load_dwordx4 v[44:47], v[2:3], off offset:48
	global_load_dwordx4 v[48:51], v[82:83], off offset:48
	global_load_dwordx4 v[52:55], v[82:83], off offset:32
	global_load_dwordx4 v[56:59], v[82:83], off offset:16
	global_load_dwordx4 v[60:63], v[82:83], off
	v_add_co_u32_e32 v122, vcc, s47, v0
	s_nop 1
	v_addc_co_u32_e32 v123, vcc, 0, v1, vcc
	global_load_dwordx4 v[124:127], v[122:123], off
	global_load_dwordx4 v[128:131], v[8:9], off offset:48
	global_load_dwordx4 v[132:135], v[8:9], off offset:32
	global_load_dwordx4 v[136:139], v[8:9], off offset:16
	s_lshl_b64 s[66:67], s[10:11], 9
	v_lshl_or_b32 v140, v66, 2, s66
	v_mov_b32_e32 v141, s67
	v_lshl_add_u64 v[142:143], s[20:21], 0, v[140:141]
	v_lshl_add_u64 v[140:141], s[22:23], 0, v[140:141]
	global_load_dwordx2 v[144:145], v[140:141], off
	global_load_dwordx2 v[146:147], v[142:143], off
	v_add_co_u32_e32 v0, vcc, s47, v0
	s_waitcnt vmcnt(17)
	v_mul_f32_e32 v2, v21, v21
	v_fmac_f32_e32 v2, v20, v20
	v_fmac_f32_e32 v2, v22, v22
	v_fmac_f32_e32 v2, v23, v23
	s_waitcnt vmcnt(16)
	v_fmac_f32_e32 v2, v24, v24
	v_fmac_f32_e32 v2, v25, v25
	v_fmac_f32_e32 v2, v26, v26
	v_fmac_f32_e32 v2, v27, v27
	s_waitcnt vmcnt(15)
	v_fmac_f32_e32 v2, v28, v28
	v_fmac_f32_e32 v2, v29, v29
	v_fmac_f32_e32 v2, v30, v30
	v_fmac_f32_e32 v2, v31, v31
	s_waitcnt vmcnt(14)
	v_fmac_f32_e32 v2, v16, v16
	v_fmac_f32_e32 v2, v17, v17
	v_fmac_f32_e32 v2, v18, v18
	v_fmac_f32_e32 v2, v19, v19
	ds_bpermute_b32 v3, v217, v2
	v_addc_co_u32_e32 v1, vcc, 0, v1, vcc
	s_waitcnt vmcnt(13)
	v_add_f32_e32 v32, 1.0, v32
	v_add_f32_e32 v33, 1.0, v33
	s_waitcnt lgkmcnt(0)
	v_add_f32_e32 v2, v2, v3
	ds_bpermute_b32 v3, v218, v2
	v_add_f32_e32 v34, 1.0, v34
	v_add_f32_e32 v35, 1.0, v35
	s_waitcnt vmcnt(10)
	v_add_f32_e32 v44, 1.0, v44
	v_add_f32_e32 v36, 1.0, v36
	s_waitcnt lgkmcnt(0)
	v_add_f32_e32 v68, v2, v3
	s_waitcnt vmcnt(2)
	v_mov_b64_e32 v[12:13], v[124:125]
	v_mov_b64_e32 v[14:15], v[126:127]
	s_nop 0
	v_mov_b64_e32 v[0:1], v[128:129]
	v_mov_b64_e32 v[2:3], v[130:131]
	v_mov_b64_e32 v[4:5], v[132:133]
	v_mov_b64_e32 v[6:7], v[134:135]
	s_nop 0
	v_mov_b64_e32 v[8:9], v[136:137]
	v_mov_b64_e32 v[10:11], v[138:139]
	ds_bpermute_b32 v94, v219, v68
	v_add_f32_e32 v37, 1.0, v37
	v_add_f32_e32 v38, 1.0, v38
	v_add_f32_e32 v39, 1.0, v39
	v_add_f32_e32 v40, 1.0, v40
	s_waitcnt lgkmcnt(0)
	v_add_f32_e32 v68, v68, v94
	ds_bpermute_b32 v94, v220, v68
	v_add_f32_e32 v41, 1.0, v41
	v_add_f32_e32 v42, 1.0, v42
	v_add_f32_e32 v43, 1.0, v43
	v_add_f32_e32 v45, 1.0, v45
	s_waitcnt lgkmcnt(0)
	v_add_f32_e32 v68, v68, v94
	ds_bpermute_b32 v94, v215, v68
	v_add_f32_e32 v46, 1.0, v46
	v_add_f32_e32 v47, 1.0, v47
	s_waitcnt lgkmcnt(0)
	v_add_f32_e32 v68, v68, v94
	ds_bpermute_b32 v94, v216, v68
	s_waitcnt lgkmcnt(0)
	v_add_f32_e32 v68, v68, v94
	v_fmamk_f32 v68, v68, 0x3a800000, v227
	v_mul_f32_e32 v94, 0x4f800000, v68
	v_cmp_gt_f32_e32 vcc, s45, v68
	s_nop 1
	v_cndmask_b32_e32 v68, v68, v94, vcc
	v_sqrt_f32_e32 v94, v68
	s_nop 0
	v_add_u32_e32 v95, -1, v94
	v_add_u32_e32 v96, 1, v94
	v_fma_f32 v97, -v95, v94, v68
	v_fma_f32 v98, -v96, v94, v68
	v_cmp_ge_f32_e64 s[8:9], 0, v97
	s_nop 1
	v_cndmask_b32_e64 v94, v94, v95, s[8:9]
	v_cmp_lt_f32_e64 s[8:9], 0, v98
	s_nop 1
	v_cndmask_b32_e64 v94, v94, v96, s[8:9]
	v_mul_f32_e32 v95, 0x37800000, v94
	v_cndmask_b32_e32 v94, v94, v95, vcc
	v_cmp_class_f32_e32 vcc, v68, v228
	s_nop 1
	v_cndmask_b32_e32 v68, v94, v68, vcc
	v_div_scale_f32 v94, s[8:9], v68, v68, 1.0
	v_rcp_f32_e32 v95, v94
	v_div_scale_f32 v96, vcc, 1.0, v68, 1.0
	s_lshl_b64 s[8:9], s[10:11], 9
	v_fma_f32 v97, -v94, v95, 1.0
	v_fmac_f32_e32 v95, v97, v95
	v_mul_f32_e32 v97, v96, v95
	v_fma_f32 v98, -v94, v97, v96
	v_fmac_f32_e32 v97, v98, v95
	v_fma_f32 v94, -v94, v97, v96
	v_div_fmas_f32 v94, v94, v95, v97
	v_div_fixup_f32 v68, v94, v68, 1.0
	v_mul_f32_e32 v20, v20, v68
	v_mul_f32_e32 v21, v21, v68
	v_mul_f32_e32 v22, v22, v68
	v_mul_f32_e32 v23, v23, v68
	v_mul_f32_e32 v16, v16, v68
	s_waitcnt vmcnt(4)
	v_mul_f32_e32 v20, v60, v20
	v_mul_f32_e32 v21, v61, v21
	v_mul_f32_e32 v24, v24, v68
	v_mul_f32_e32 v25, v25, v68
	v_mul_f32_e32 v22, v62, v22
	v_mul_f32_e32 v23, v63, v23
	v_mul_f32_e32 v16, v16, v48
	s_waitcnt vmcnt(3)
	v_fma_f32 v12, v32, v20, v12
	v_fma_f32 v13, v33, v21, v13
	v_mul_f32_e32 v26, v26, v68
	v_mul_f32_e32 v27, v27, v68
	v_mul_f32_e32 v24, v56, v24
	v_mul_f32_e32 v25, v57, v25
	v_fma_f32 v14, v34, v22, v14
	v_fmac_f32_e32 v15, v35, v23
	s_waitcnt vmcnt(2)
	v_fma_f32 v16, v16, v44, v0
	v_max3_f32 v0, |v12|, 0, |v13|
	v_mul_f32_e32 v28, v28, v68
	v_mul_f32_e32 v29, v29, v68
	v_mul_f32_e32 v26, v26, v58
	v_mul_f32_e32 v27, v27, v59
	s_waitcnt vmcnt(0)
; __device__ __forceinline__ void phase10(const Args& a, LAS unsigned char* lds, int tid, int wave, int lane, int vcu, int G, int emask, bool probe) {
;     ...
;                 float h2[16], am = 0.f;
; #pragma unroll
;                 for (int e = 0; e < 16; ++e) { const int c = c0 + e; h2[e] = x1v[e] * rstd * a.in[16][c] * (1.f + mrow[4096 + c]) + mrow[3072 + c]; am = fmaxf(am, fabsf(h2[e])); }
; #pragma unroll
;                 for (int o = 1; o < 64; o <<= 1) am = fmaxf(am, __shfl_xor(am, o));
;                 const float inv = am > 0.f ? 127.f / am : 0.f; sh[tk] = am * (1.f / 127.f);
; #pragma unroll
;                 for (int q = 0; q < 4; ++q) { unsigned pk = 0;
; #pragma unroll
;                     for (int e = 0; e < 4; ++e) pk |= ((unsigned)(int)rintf(h2[4 * q + e] * inv) & 0xffu) << (8 * e);
;                     hq[tk][q] = pk; }
;                 const int e0 = SEL_E[R * 128 + 2 * lane], e1 = SEL_E[R * 128 + 2 * lane + 1]; const float g0 = SEL_G[R * 128 + 2 * lane], g1 = SEL_G[R * 128 + 2 * lane + 1];
	v_fma_f32 v8, v36, v24, v8
	v_fma_f32 v9, v37, v25, v9
	v_max3_f32 v0, v0, |v14|, |v15|
	v_mul_f32_e32 v30, v30, v68
	v_mul_f32_e32 v31, v31, v68
	v_mul_f32_e32 v28, v28, v52
	v_mul_f32_e32 v29, v29, v53
	v_fma_f32 v10, v26, v38, v10
	v_fmac_f32_e32 v11, v27, v39
	v_max3_f32 v0, v0, |v8|, |v9|
	v_mul_f32_e32 v17, v17, v68
	v_mul_f32_e32 v30, v30, v54
	v_mul_f32_e32 v31, v31, v55
	v_fma_f32 v20, v28, v40, v4
	v_fma_f32 v21, v29, v41, v5
	v_max3_f32 v0, v0, |v10|, |v11|
	v_mul_f32_e32 v18, v18, v68
	v_mul_f32_e32 v19, v19, v68
	v_mul_f32_e32 v17, v17, v49
	v_fma_f32 v6, v30, v42, v6
	v_fmac_f32_e32 v7, v31, v43
	v_max3_f32 v0, v0, |v20|, |v21|
	v_mul_f32_e32 v18, v18, v50
	v_mul_f32_e32 v19, v19, v51
	v_fma_f32 v17, v17, v45, v1
	v_max3_f32 v0, v0, |v6|, |v7|
	v_fma_f32 v2, v18, v46, v2
	v_fmac_f32_e32 v3, v19, v47
	v_max3_f32 v0, v0, |v16|, |v17|
	v_max3_f32 v0, v0, |v2|, |v3|
	ds_bpermute_b32 v1, v217, v0
	s_waitcnt lgkmcnt(0)
	v_max_f32_e32 v1, v1, v1
	v_max_f32_e32 v0, v0, v1
	ds_bpermute_b32 v1, v218, v0
	s_waitcnt lgkmcnt(0)
	v_max_f32_e32 v1, v1, v1
	v_max_f32_e32 v0, v0, v1
	ds_bpermute_b32 v1, v219, v0
	s_waitcnt lgkmcnt(0)
	v_max_f32_e32 v1, v1, v1
	v_max_f32_e32 v0, v0, v1
	ds_bpermute_b32 v1, v220, v0
	s_waitcnt lgkmcnt(0)
	v_max_f32_e32 v1, v1, v1
	v_max_f32_e32 v4, v0, v1
	ds_bpermute_b32 v5, v215, v4
	v_lshl_or_b32 v0, v66, 2, s8
	v_mov_b32_e32 v1, s9
	s_waitcnt lgkmcnt(0)
	v_max_f32_e32 v5, v5, v5
	v_max_f32_e32 v18, v4, v5
	v_lshl_add_u64 v[4:5], s[20:21], 0, v[0:1]
	v_lshl_add_u64 v[0:1], s[22:23], 0, v[0:1]
	s_waitcnt vmcnt(0)
	v_mov_b64_e32 v[0:1], v[144:145]
	s_nop 0
	v_mov_b64_e32 v[4:5], v[146:147]
	ds_bpermute_b32 v19, v216, v18
	s_waitcnt lgkmcnt(0)
	v_max_f32_e32 v19, v19, v19
	v_max_f32_e32 v18, v18, v19
	v_div_scale_f32 v19, s[8:9], v18, v18, s48
	v_rcp_f32_e32 v22, v19
	v_div_scale_f32 v23, vcc, s48, v18, s48
	v_mul_f32_e32 v54, 0x3c010204, v18
	v_fma_f32 v24, -v19, v22, 1.0
	v_fmac_f32_e32 v22, v24, v22
	v_mul_f32_e32 v24, v23, v22
	v_fma_f32 v25, -v19, v24, v23
	v_fmac_f32_e32 v24, v25, v22
	v_fma_f32 v19, -v19, v24, v23
	v_div_fmas_f32 v19, v19, v22, v24
	v_div_fixup_f32 v19, v19, v18, s48
	v_cmp_lt_f32_e32 vcc, 0, v18
	s_waitcnt vmcnt(0)
; __device__ __forceinline__ void phase10(const Args& a, LAS unsigned char* lds, int tid, int wave, int lane, int vcu, int G, int emask, bool probe) {
;     ...
;                 const float inv = am > 0.f ? 127.f / am : 0.f; sh[tk] = am * (1.f / 127.f);
; #pragma unroll
;                 for (int q = 0; q < 4; ++q) { unsigned pk = 0;
; #pragma unroll
;                     for (int e = 0; e < 4; ++e) pk |= ((unsigned)(int)rintf(h2[4 * q + e] * inv) & 0xffu) << (8 * e);
;                     hq[tk][q] = pk; }
;                 const int e0 = SEL_E[R * 128 + 2 * lane], e1 = SEL_E[R * 128 + 2 * lane + 1]; const float g0 = SEL_G[R * 128 + 2 * lane], g1 = SEL_G[R * 128 + 2 * lane + 1];
;                 const int r0 = e0 >> 11, r1 = e1 >> 11; int pos0 = 0, pos1 = 0, off = 0;
;                 const unsigned long long lt = (1ull << lane) - 1ull;
;                 for (int r = 0; r < NRANGE; ++r) {
;                     const unsigned long long m0 = __ballot(r0 == r), m1 = __ballot(r1 == r);
;                     if (r0 == r) pos0 = off + __popcll(m0 & lt);
;                     if (r1 == r) pos1 = off + __popcll(m0) + __popcll(m1 & lt);
;                     off += __popcll(m0) + __popcll(m1);
;                 }
;                 PE[tk * 128 + pos0] = (unsigned short)e0; PE[tk * 128 + pos1] = (unsigned short)e1; PG[tk * 128 + pos0] = g0; PG[tk * 128 + pos1] = g1;
	v_cmp_gt_u32_e64 s[8:9], s50, v5
	v_cndmask_b32_e32 v18, 0, v19, vcc
	v_mul_f32_e32 v9, v9, v18
	v_mul_f32_e32 v8, v8, v18
	v_mul_f32_e32 v10, v10, v18
	v_mul_f32_e32 v11, v11, v18
	v_rndne_f32_e32 v9, v9
	v_rndne_f32_e32 v8, v8
	v_rndne_f32_e32 v10, v10
	v_rndne_f32_e32 v11, v11
	v_cvt_i32_f32_e32 v9, v9
	v_cvt_i32_f32_e32 v8, v8
	v_cvt_i32_f32_sdwa v10, v10 dst_sel:WORD_1 dst_unused:UNUSED_PAD src0_sel:DWORD
	v_cvt_i32_f32_e32 v11, v11
	v_lshlrev_b32_e32 v9, 8, v9
	v_and_b32_e32 v9, 0xff00, v9
	v_and_b32_e32 v10, 0xff0000, v10
	v_perm_b32 v8, v11, v8, s49
	v_or3_b32 v48, v8, v9, v10
	v_mul_f32_e32 v9, v21, v18
	v_mul_f32_e32 v19, v20, v18
	v_rndne_f32_e32 v9, v9
	v_mul_f32_e32 v6, v6, v18
	v_mul_f32_e32 v7, v7, v18
	v_rndne_f32_e32 v8, v19
	v_cvt_i32_f32_e32 v9, v9
	v_rndne_f32_e32 v6, v6
	v_rndne_f32_e32 v7, v7
	v_cvt_i32_f32_e32 v8, v8
	v_cvt_i32_f32_sdwa v6, v6 dst_sel:WORD_1 dst_unused:UNUSED_PAD src0_sel:DWORD
	v_cvt_i32_f32_e32 v7, v7
	v_lshlrev_b32_e32 v9, 8, v9
	v_and_b32_e32 v9, 0xff00, v9
	v_and_b32_e32 v6, 0xff0000, v6
	v_perm_b32 v7, v7, v8, s49
	v_or3_b32 v51, v7, v9, v6
	v_mul_f32_e32 v7, v17, v18
	v_mul_f32_e32 v6, v16, v18
	v_rndne_f32_e32 v7, v7
	v_mul_f32_e32 v2, v2, v18
	v_mul_f32_e32 v3, v3, v18
	v_rndne_f32_e32 v6, v6
	v_cvt_i32_f32_e32 v7, v7
	v_rndne_f32_e32 v2, v2
	v_rndne_f32_e32 v3, v3
	v_cvt_i32_f32_e32 v6, v6
	v_cvt_i32_f32_sdwa v2, v2 dst_sel:WORD_1 dst_unused:UNUSED_PAD src0_sel:DWORD
	v_cvt_i32_f32_e32 v3, v3
	v_lshlrev_b32_e32 v7, 8, v7
	v_and_b32_e32 v7, 0xff00, v7
	v_and_b32_e32 v2, 0xff0000, v2
	v_perm_b32 v3, v3, v6, s49
	v_cmp_gt_u32_e32 vcc, s50, v4
	v_or3_b32 v49, v3, v7, v2
	v_and_b32_e32 v8, s8, v74
	v_and_b32_e32 v7, vcc_lo, v74
	v_and_b32_e32 v6, vcc_hi, v65
	v_bcnt_u32_b32 v7, v7, 0
	v_ashrrev_i32_e32 v3, 11, v4
	v_bcnt_u32_b32 v6, v6, v7
	v_and_b32_e32 v7, s9, v65
	v_bcnt_u32_b32 v8, v8, 0
	v_cndmask_b32_e32 v6, 0, v6, vcc
	s_bcnt1_i32_b64 s10, vcc
	v_bcnt_u32_b32 v7, v7, v8
	v_cmp_eq_u32_e32 vcc, 1, v3
	v_add_u32_e32 v7, s10, v7
	v_ashrrev_i32_e32 v2, 11, v5
	v_and_b32_e32 v9, vcc_lo, v74
	v_cndmask_b32_e64 v7, 0, v7, s[8:9]
	s_bcnt1_i32_b64 s8, s[8:9]
	v_and_b32_e32 v8, vcc_hi, v65
	v_bcnt_u32_b32 v9, v9, 0
	s_add_i32 s10, s8, s10
	v_cmp_eq_u32_e64 s[8:9], 1, v2
	v_bcnt_u32_b32 v8, v8, v9
	v_add_u32_e32 v8, s10, v8
	v_and_b32_e32 v9, s8, v74
	v_cndmask_b32_e32 v6, v6, v8, vcc
	s_bcnt1_i32_b64 s11, vcc
	v_and_b32_e32 v8, s9, v65
	v_bcnt_u32_b32 v9, v9, 0
	s_add_i32 s10, s10, s11
	v_bcnt_u32_b32 v8, v8, v9
	v_cmp_eq_u32_e32 vcc, 2, v3
	v_add_u32_e32 v8, s10, v8
	v_cndmask_b32_e64 v7, v7, v8, s[8:9]
	v_and_b32_e32 v9, vcc_lo, v74
	s_bcnt1_i32_b64 s8, s[8:9]
	v_and_b32_e32 v8, vcc_hi, v65
	v_bcnt_u32_b32 v9, v9, 0
	s_add_i32 s10, s10, s8
	v_cmp_eq_u32_e64 s[8:9], 2, v2
	v_bcnt_u32_b32 v8, v8, v9
	v_add_u32_e32 v8, s10, v8
	v_and_b32_e32 v9, s8, v74
	v_cndmask_b32_e32 v6, v6, v8, vcc
	s_bcnt1_i32_b64 s11, vcc
	v_and_b32_e32 v8, s9, v65
	v_bcnt_u32_b32 v9, v9, 0
	s_add_i32 s10, s10, s11
	v_bcnt_u32_b32 v8, v8, v9
	v_cmp_eq_u32_e32 vcc, 3, v3
	v_add_u32_e32 v8, s10, v8
	v_cndmask_b32_e64 v7, v7, v8, s[8:9]
	v_and_b32_e32 v9, vcc_lo, v74
	s_bcnt1_i32_b64 s8, s[8:9]
	v_and_b32_e32 v8, vcc_hi, v65
	v_bcnt_u32_b32 v9, v9, 0
	s_add_i32 s10, s10, s8
	v_cmp_eq_u32_e64 s[8:9], 3, v2
	v_bcnt_u32_b32 v8, v8, v9
	v_add_u32_e32 v8, s10, v8
	v_and_b32_e32 v9, s8, v74
	v_cndmask_b32_e32 v6, v6, v8, vcc
	s_bcnt1_i32_b64 s11, vcc
	v_and_b32_e32 v8, s9, v65
	v_bcnt_u32_b32 v9, v9, 0
	s_add_i32 s10, s10, s11
	v_bcnt_u32_b32 v8, v8, v9
	v_cmp_eq_u32_e32 vcc, 4, v3
	v_add_u32_e32 v8, s10, v8
	v_cndmask_b32_e64 v7, v7, v8, s[8:9]
	v_and_b32_e32 v9, vcc_lo, v74
	s_bcnt1_i32_b64 s8, s[8:9]
	v_and_b32_e32 v8, vcc_hi, v65
	v_bcnt_u32_b32 v9, v9, 0
	s_add_i32 s10, s10, s8
	v_cmp_eq_u32_e64 s[8:9], 4, v2
	v_bcnt_u32_b32 v8, v8, v9
	v_add_u32_e32 v8, s10, v8
	v_and_b32_e32 v9, s8, v74
	v_cndmask_b32_e32 v6, v6, v8, vcc
	s_bcnt1_i32_b64 s11, vcc
	v_and_b32_e32 v8, s9, v65
	v_bcnt_u32_b32 v9, v9, 0
	s_add_i32 s10, s10, s11
	v_bcnt_u32_b32 v8, v8, v9
	v_cmp_eq_u32_e32 vcc, 5, v3
	v_add_u32_e32 v8, s10, v8
	v_cndmask_b32_e64 v7, v7, v8, s[8:9]
	v_and_b32_e32 v9, vcc_lo, v74
	s_bcnt1_i32_b64 s8, s[8:9]
	v_and_b32_e32 v8, vcc_hi, v65
	v_bcnt_u32_b32 v9, v9, 0
	s_add_i32 s10, s10, s8
	v_cmp_eq_u32_e64 s[8:9], 5, v2
	v_bcnt_u32_b32 v8, v8, v9
	v_add_u32_e32 v8, s10, v8
	v_and_b32_e32 v9, s8, v74
	v_cndmask_b32_e32 v6, v6, v8, vcc
	s_bcnt1_i32_b64 s11, vcc
	v_and_b32_e32 v8, s9, v65
	v_bcnt_u32_b32 v9, v9, 0
	s_add_i32 s10, s10, s11
	v_bcnt_u32_b32 v8, v8, v9
	v_cmp_eq_u32_e32 vcc, 6, v3
	v_add_u32_e32 v8, s10, v8
	v_cndmask_b32_e64 v7, v7, v8, s[8:9]
	v_and_b32_e32 v9, vcc_lo, v74
	s_bcnt1_i32_b64 s8, s[8:9]
	v_and_b32_e32 v8, vcc_hi, v65
	v_bcnt_u32_b32 v9, v9, 0
	s_add_i32 s10, s10, s8
	v_cmp_eq_u32_e64 s[8:9], 6, v2
	v_bcnt_u32_b32 v8, v8, v9
	v_add_u32_e32 v8, s10, v8
	v_and_b32_e32 v9, s8, v74
	v_cndmask_b32_e32 v6, v6, v8, vcc
	s_bcnt1_i32_b64 s11, vcc
	v_and_b32_e32 v8, s9, v65
	v_bcnt_u32_b32 v9, v9, 0
	s_add_i32 s10, s10, s11
	v_bcnt_u32_b32 v8, v8, v9
	v_add_u32_e32 v8, s10, v8
	v_cndmask_b32_e64 v7, v7, v8, s[8:9]
	s_bcnt1_i32_b64 s8, s[8:9]
	s_add_i32 s10, s10, s8
	v_cmp_eq_u32_e64 s[8:9], 7, v3
	v_cmp_eq_u32_e32 vcc, 7, v2
	v_mul_f32_e32 v13, v13, v18
	v_and_b32_e32 v3, s8, v74
	v_and_b32_e32 v2, s9, v65
	v_bcnt_u32_b32 v3, v3, 0
	v_bcnt_u32_b32 v2, v2, v3
	v_add_u32_e32 v2, s10, v2
	v_mul_f32_e32 v12, v12, v18
	v_mul_f32_e32 v14, v14, v18
	v_mul_f32_e32 v15, v15, v18
	v_rndne_f32_e32 v13, v13
	v_cndmask_b32_e64 v2, v6, v2, s[8:9]
	v_and_b32_e32 v6, vcc_lo, v74
	v_rndne_f32_e32 v12, v12
	v_rndne_f32_e32 v14, v14
	v_rndne_f32_e32 v15, v15
	v_cvt_i32_f32_e32 v13, v13
	s_bcnt1_i32_b64 s8, s[8:9]
	v_and_b32_e32 v3, vcc_hi, v65
	v_bcnt_u32_b32 v6, v6, 0
	v_cvt_i32_f32_e32 v12, v12
	v_cvt_i32_f32_sdwa v14, v14 dst_sel:WORD_1 dst_unused:UNUSED_PAD src0_sel:DWORD
	v_cvt_i32_f32_e32 v15, v15
	s_add_i32 s10, s10, s8
	v_bcnt_u32_b32 v3, v3, v6
	v_add_u32_e32 v3, s10, v3
	v_cndmask_b32_e32 v3, v7, v3, vcc
	v_lshlrev_b32_e32 v2, 1, v2
	v_lshlrev_b32_e32 v13, 8, v13
	v_add_u32_e32 v6, s39, v2
	v_lshlrev_b32_e32 v3, 1, v3
	v_and_b32_e32 v14, 0xff0000, v14
	v_perm_b32 v12, v15, v12, s49
	v_and_b32_e32 v11, 0xff00, v13
	ds_write_b16 v6, v4
	v_add_u32_e32 v4, s39, v3
	v_add_u32_e32 v2, v6, v2
	v_or3_b32 v50, v12, v11, v14
	ds_write_b32 v2, v0 offset:1024
	v_add_u32_e32 v0, v4, v3
	ds_write_b16 v4, v5
	ds_write_b32 v0, v1 offset:1024
	s_branch .LBB0_1675

; __device__ __forceinline__ void phase10(const Args& a, LAS unsigned char* lds, int tid, int wave, int lane, int vcu, int G, int emask, bool probe) {
;     ...
;                 const int brow = R < NP ? 0 : 1 + (int)((R - NP) >> 3);
;                 const float* mrow = mod + (size_t)brow * 6144;
;                 float x1v[16];
; #pragma unroll
;                 for (int q = 0; q < 4; ++q) { const f32x4 t4 = *(const f32x4*)(X1 + R * DM + c0 + 4 * q);
; #pragma unroll
;                     for (int e = 0; e < 4; ++e) x1v[4 * q + e] = t4[e]; }
;                 float ss = 0.f;
; #pragma unroll
;                 for (int e = 0; e < 16; ++e) ss += x1v[e] * x1v[e];
;                 const float rstd = 1.0f / sqrtf(wave_sum(ss) * (1.f / DM) + EPS);
;                 float h2[16], am = 0.f;
; #pragma unroll
;                 for (int e = 0; e < 16; ++e) { const int c = c0 + e; h2[e] = x1v[e] * rstd * a.in[16][c] * (1.f + mrow[4096 + c]) + mrow[3072 + c]; am = fmaxf(am, fabsf(h2[e])); }
; #pragma unroll
;                 for (int o = 1; o < 64; o <<= 1) am = fmaxf(am, __shfl_xor(am, o));
;                 const float inv = am > 0.f ? 127.f / am : 0.f; sh[tk] = am * (1.f / 127.f);
; #pragma unroll
;                 for (int q = 0; q < 4; ++q) { unsigned pk = 0;
; #pragma unroll
;                     for (int e = 0; e < 4; ++e) pk |= ((unsigned)(int)rintf(h2[4 * q + e] * inv) & 0xffu) << (8 * e);
;                     hq[tk][q] = pk; }
;                 const int e0 = SEL_E[R * 128 + 2 * lane], e1 = SEL_E[R * 128 + 2 * lane + 1]; const float g0 = SEL_G[R * 128 + 2 * lane], g1 = SEL_G[R * 128 + 2 * lane + 1];
.LBB0_1685:
	s_lshl_b64 s[62:63], s[34:35], 12
	v_lshl_add_u64 v[0:1], v[72:73], 0, s[62:63]
	s_waitcnt lgkmcnt(10)
	global_load_dwordx4 v[20:23], v[0:1], off
	s_waitcnt lgkmcnt(4)
	global_load_dwordx4 v[24:27], v[0:1], off offset:16
	global_load_dwordx4 v[28:31], v[0:1], off offset:32
	global_load_dwordx4 v[16:19], v[0:1], off offset:48
	v_lshl_add_u64 v[0:1], s[10:11], 2, v[86:87]
	v_add_co_u32_e32 v2, vcc, s46, v0
	v_lshl_add_u64 v[8:9], v[0:1], 0, s[28:29]
	s_nop 0
	v_addc_co_u32_e32 v3, vcc, 0, v1, vcc
	global_load_dwordx4 v[32:35], v[2:3], off
	v_lshl_add_u64 v[2:3], v[0:1], 0, s[26:27]
	global_load_dwordx4 v[36:39], v[2:3], off offset:16
	global_load_dwordx4 v[40:43], v[2:3], off offset:32
	global_load_dwordx4 v[44:47], v[2:3], off offset:48
	global_load_dwordx4 v[56:59], v[82:83], off offset:48
	global_load_dwordx4 v[60:63], v[82:83], off offset:32
	global_load_dwordx4 v[94:97], v[82:83], off offset:16
	s_waitcnt lgkmcnt(6)
	global_load_dwordx4 v[98:101], v[82:83], off
	v_add_co_u32_e32 v122, vcc, s47, v0
	s_nop 1
	v_addc_co_u32_e32 v123, vcc, 0, v1, vcc
	global_load_dwordx4 v[124:127], v[122:123], off
	global_load_dwordx4 v[128:131], v[8:9], off offset:48
	global_load_dwordx4 v[132:135], v[8:9], off offset:32
	global_load_dwordx4 v[136:139], v[8:9], off offset:16
	s_lshl_b64 s[66:67], s[34:35], 9
	v_lshl_or_b32 v140, v66, 2, s66
	v_mov_b32_e32 v141, s67
	v_lshl_add_u64 v[142:143], s[20:21], 0, v[140:141]
	v_lshl_add_u64 v[140:141], s[22:23], 0, v[140:141]
	global_load_dwordx2 v[144:145], v[140:141], off
	global_load_dwordx2 v[146:147], v[142:143], off
	v_add_co_u32_e32 v0, vcc, s47, v0
	s_waitcnt vmcnt(17)
	v_mul_f32_e32 v2, v21, v21
	v_fmac_f32_e32 v2, v20, v20
	v_fmac_f32_e32 v2, v22, v22
	v_fmac_f32_e32 v2, v23, v23
	s_waitcnt vmcnt(16)
	v_fmac_f32_e32 v2, v24, v24
	v_fmac_f32_e32 v2, v25, v25
	v_fmac_f32_e32 v2, v26, v26
	v_fmac_f32_e32 v2, v27, v27
	s_waitcnt vmcnt(15)
	v_fmac_f32_e32 v2, v28, v28
	v_fmac_f32_e32 v2, v29, v29
	v_fmac_f32_e32 v2, v30, v30
	v_fmac_f32_e32 v2, v31, v31
	s_waitcnt vmcnt(14)
	v_fmac_f32_e32 v2, v16, v16
	v_fmac_f32_e32 v2, v17, v17
	v_fmac_f32_e32 v2, v18, v18
	v_fmac_f32_e32 v2, v19, v19
	ds_bpermute_b32 v3, v217, v2
	v_addc_co_u32_e32 v1, vcc, 0, v1, vcc
	s_waitcnt vmcnt(13)
	v_add_f32_e32 v32, 1.0, v32
	v_add_f32_e32 v33, 1.0, v33
	s_waitcnt lgkmcnt(0)
	v_add_f32_e32 v2, v2, v3
	ds_bpermute_b32 v3, v218, v2
	v_add_f32_e32 v34, 1.0, v34
	v_add_f32_e32 v35, 1.0, v35
	s_waitcnt vmcnt(10)
	v_add_f32_e32 v44, 1.0, v44
	v_add_f32_e32 v36, 1.0, v36
	s_waitcnt lgkmcnt(0)
	v_add_f32_e32 v52, v2, v3
	s_waitcnt vmcnt(2)
	v_mov_b64_e32 v[12:13], v[124:125]
	v_mov_b64_e32 v[14:15], v[126:127]
	s_nop 0
	v_mov_b64_e32 v[0:1], v[128:129]
	v_mov_b64_e32 v[2:3], v[130:131]
	v_mov_b64_e32 v[4:5], v[132:133]
	v_mov_b64_e32 v[6:7], v[134:135]
	s_nop 0
	v_mov_b64_e32 v[8:9], v[136:137]
	v_mov_b64_e32 v[10:11], v[138:139]
	ds_bpermute_b32 v53, v219, v52
	v_add_f32_e32 v37, 1.0, v37
	v_add_f32_e32 v38, 1.0, v38
	v_add_f32_e32 v39, 1.0, v39
	v_add_f32_e32 v40, 1.0, v40
	s_waitcnt lgkmcnt(0)
	v_add_f32_e32 v52, v52, v53
	ds_bpermute_b32 v53, v220, v52
	v_add_f32_e32 v41, 1.0, v41
	v_add_f32_e32 v42, 1.0, v42
	v_add_f32_e32 v43, 1.0, v43
	v_add_f32_e32 v45, 1.0, v45
	s_waitcnt lgkmcnt(0)
	v_add_f32_e32 v52, v52, v53
	ds_bpermute_b32 v53, v215, v52
	v_add_f32_e32 v46, 1.0, v46
	v_add_f32_e32 v47, 1.0, v47
	s_waitcnt lgkmcnt(0)
	v_add_f32_e32 v52, v52, v53
	ds_bpermute_b32 v53, v216, v52
	s_waitcnt lgkmcnt(0)
	v_add_f32_e32 v52, v52, v53
	v_fmamk_f32 v52, v52, 0x3a800000, v227
	v_mul_f32_e32 v53, 0x4f800000, v52
	v_cmp_gt_f32_e32 vcc, s45, v52
	s_nop 1
	v_cndmask_b32_e32 v52, v52, v53, vcc
	v_sqrt_f32_e32 v53, v52
	s_nop 0
	v_add_u32_e32 v55, -1, v53
	v_add_u32_e32 v68, 1, v53
	v_fma_f32 v102, -v55, v53, v52
	v_fma_f32 v103, -v68, v53, v52
	v_cmp_ge_f32_e64 s[10:11], 0, v102
	s_nop 1
	v_cndmask_b32_e64 v53, v53, v55, s[10:11]
	v_cmp_lt_f32_e64 s[10:11], 0, v103
	s_nop 1
	v_cndmask_b32_e64 v53, v53, v68, s[10:11]
	v_mul_f32_e32 v55, 0x37800000, v53
	v_cndmask_b32_e32 v53, v53, v55, vcc
	v_cmp_class_f32_e32 vcc, v52, v228
	s_nop 1
	v_cndmask_b32_e32 v52, v53, v52, vcc
	v_div_scale_f32 v53, s[10:11], v52, v52, 1.0
	v_rcp_f32_e32 v55, v53
	v_div_scale_f32 v68, vcc, 1.0, v52, 1.0
	s_lshl_b64 s[10:11], s[34:35], 9
	v_fma_f32 v102, -v53, v55, 1.0
	v_fmac_f32_e32 v55, v102, v55
	v_mul_f32_e32 v102, v68, v55
	v_fma_f32 v103, -v53, v102, v68
	v_fmac_f32_e32 v102, v103, v55
	v_fma_f32 v53, -v53, v102, v68
	v_div_fmas_f32 v53, v53, v55, v102
	v_div_fixup_f32 v52, v53, v52, 1.0
	v_mul_f32_e32 v20, v20, v52
	v_mul_f32_e32 v21, v21, v52
	v_mul_f32_e32 v22, v22, v52
	v_mul_f32_e32 v23, v23, v52
	v_mul_f32_e32 v16, v16, v52
	s_waitcnt vmcnt(4)
	v_mul_f32_e32 v20, v98, v20
	v_mul_f32_e32 v21, v99, v21
	v_mul_f32_e32 v24, v24, v52
	v_mul_f32_e32 v25, v25, v52
	v_mul_f32_e32 v22, v100, v22
	v_mul_f32_e32 v23, v101, v23
	v_mul_f32_e32 v16, v16, v56
	s_waitcnt vmcnt(3)
	v_fma_f32 v12, v32, v20, v12
	v_fma_f32 v13, v33, v21, v13
	v_mul_f32_e32 v26, v26, v52
	v_mul_f32_e32 v27, v27, v52
	v_mul_f32_e32 v24, v94, v24
	v_mul_f32_e32 v25, v95, v25
	v_fma_f32 v14, v34, v22, v14
	v_fmac_f32_e32 v15, v35, v23
	s_waitcnt vmcnt(2)
	v_fma_f32 v16, v16, v44, v0
	v_max3_f32 v0, |v12|, 0, |v13|
	v_mul_f32_e32 v28, v28, v52
	v_mul_f32_e32 v29, v29, v52
	v_mul_f32_e32 v26, v26, v96
	v_mul_f32_e32 v27, v27, v97
	s_waitcnt vmcnt(0)
; __device__ __forceinline__ void phase10(const Args& a, LAS unsigned char* lds, int tid, int wave, int lane, int vcu, int G, int emask, bool probe) {
;     ...
;                 float h2[16], am = 0.f;
; #pragma unroll
;                 for (int e = 0; e < 16; ++e) { const int c = c0 + e; h2[e] = x1v[e] * rstd * a.in[16][c] * (1.f + mrow[4096 + c]) + mrow[3072 + c]; am = fmaxf(am, fabsf(h2[e])); }
; #pragma unroll
;                 for (int o = 1; o < 64; o <<= 1) am = fmaxf(am, __shfl_xor(am, o));
;                 const float inv = am > 0.f ? 127.f / am : 0.f; sh[tk] = am * (1.f / 127.f);
; #pragma unroll
;                 for (int q = 0; q < 4; ++q) { unsigned pk = 0;
; #pragma unroll
;                     for (int e = 0; e < 4; ++e) pk |= ((unsigned)(int)rintf(h2[4 * q + e] * inv) & 0xffu) << (8 * e);
;                     hq[tk][q] = pk; }
;                 const int e0 = SEL_E[R * 128 + 2 * lane], e1 = SEL_E[R * 128 + 2 * lane + 1]; const float g0 = SEL_G[R * 128 + 2 * lane], g1 = SEL_G[R * 128 + 2 * lane + 1];
	v_fma_f32 v8, v36, v24, v8
	v_fma_f32 v9, v37, v25, v9
	v_max3_f32 v0, v0, |v14|, |v15|
	v_mul_f32_e32 v30, v30, v52
	v_mul_f32_e32 v31, v31, v52
	v_mul_f32_e32 v28, v28, v60
	v_mul_f32_e32 v29, v29, v61
	v_fma_f32 v10, v26, v38, v10
	v_fmac_f32_e32 v11, v27, v39
	v_max3_f32 v0, v0, |v8|, |v9|
	v_mul_f32_e32 v17, v17, v52
	v_mul_f32_e32 v30, v30, v62
	v_mul_f32_e32 v31, v31, v63
	v_fma_f32 v20, v28, v40, v4
	v_fma_f32 v21, v29, v41, v5
	v_max3_f32 v0, v0, |v10|, |v11|
	v_mul_f32_e32 v18, v18, v52
	v_mul_f32_e32 v19, v19, v52
	v_mul_f32_e32 v17, v17, v57
	v_fma_f32 v6, v30, v42, v6
	v_fmac_f32_e32 v7, v31, v43
	v_max3_f32 v0, v0, |v20|, |v21|
	v_mul_f32_e32 v18, v18, v58
	v_mul_f32_e32 v19, v19, v59
	v_fma_f32 v17, v17, v45, v1
	v_max3_f32 v0, v0, |v6|, |v7|
	v_fma_f32 v2, v18, v46, v2
	v_fmac_f32_e32 v3, v19, v47
	v_max3_f32 v0, v0, |v16|, |v17|
	v_max3_f32 v0, v0, |v2|, |v3|
	ds_bpermute_b32 v1, v217, v0
	s_waitcnt lgkmcnt(0)
	v_max_f32_e32 v1, v1, v1
	v_max_f32_e32 v0, v0, v1
	ds_bpermute_b32 v1, v218, v0
	s_waitcnt lgkmcnt(0)
	v_max_f32_e32 v1, v1, v1
	v_max_f32_e32 v0, v0, v1
	ds_bpermute_b32 v1, v219, v0
	s_waitcnt lgkmcnt(0)
	v_max_f32_e32 v1, v1, v1
	v_max_f32_e32 v0, v0, v1
	ds_bpermute_b32 v1, v220, v0
	s_waitcnt lgkmcnt(0)
	v_max_f32_e32 v1, v1, v1
	v_max_f32_e32 v4, v0, v1
	ds_bpermute_b32 v5, v215, v4
	v_lshl_or_b32 v0, v66, 2, s10
	v_mov_b32_e32 v1, s11
	s_waitcnt lgkmcnt(0)
	v_max_f32_e32 v5, v5, v5
	v_max_f32_e32 v18, v4, v5
	v_lshl_add_u64 v[4:5], s[20:21], 0, v[0:1]
	v_lshl_add_u64 v[0:1], s[22:23], 0, v[0:1]
	s_waitcnt vmcnt(0)
	v_mov_b64_e32 v[0:1], v[144:145]
	s_nop 0
	v_mov_b64_e32 v[4:5], v[146:147]
	ds_bpermute_b32 v19, v216, v18
	s_waitcnt lgkmcnt(0)
	v_max_f32_e32 v19, v19, v19
	v_max_f32_e32 v18, v18, v19
	v_div_scale_f32 v19, s[10:11], v18, v18, s48
	v_rcp_f32_e32 v22, v19
	v_div_scale_f32 v23, vcc, s48, v18, s48
	v_mul_f32_e32 v55, 0x3c010204, v18
	v_fma_f32 v24, -v19, v22, 1.0
	v_fmac_f32_e32 v22, v24, v22
	v_mul_f32_e32 v24, v23, v22
	v_fma_f32 v25, -v19, v24, v23
	v_fmac_f32_e32 v24, v25, v22
	v_fma_f32 v19, -v19, v24, v23
	v_div_fmas_f32 v19, v19, v22, v24
	v_div_fixup_f32 v19, v19, v18, s48
	v_cmp_lt_f32_e32 vcc, 0, v18
	s_waitcnt vmcnt(0)
; __device__ __forceinline__ void phase10(const Args& a, LAS unsigned char* lds, int tid, int wave, int lane, int vcu, int G, int emask, bool probe) {
;     ...
;                 const float inv = am > 0.f ? 127.f / am : 0.f; sh[tk] = am * (1.f / 127.f);
; #pragma unroll
;                 for (int q = 0; q < 4; ++q) { unsigned pk = 0;
; #pragma unroll
;                     for (int e = 0; e < 4; ++e) pk |= ((unsigned)(int)rintf(h2[4 * q + e] * inv) & 0xffu) << (8 * e);
;                     hq[tk][q] = pk; }
;                 const int e0 = SEL_E[R * 128 + 2 * lane], e1 = SEL_E[R * 128 + 2 * lane + 1]; const float g0 = SEL_G[R * 128 + 2 * lane], g1 = SEL_G[R * 128 + 2 * lane + 1];
;                 const int r0 = e0 >> 11, r1 = e1 >> 11; int pos0 = 0, pos1 = 0, off = 0;
;                 const unsigned long long lt = (1ull << lane) - 1ull;
;                 for (int r = 0; r < NRANGE; ++r) {
;                     const unsigned long long m0 = __ballot(r0 == r), m1 = __ballot(r1 == r);
;                     if (r0 == r) pos0 = off + __popcll(m0 & lt);
;                     if (r1 == r) pos1 = off + __popcll(m0) + __popcll(m1 & lt);
;                     off += __popcll(m0) + __popcll(m1);
;                 }
;                 PE[tk * 128 + pos0] = (unsigned short)e0; PE[tk * 128 + pos1] = (unsigned short)e1; PG[tk * 128 + pos0] = g0; PG[tk * 128 + pos1] = g1;
	v_cmp_gt_u32_e64 s[10:11], s50, v5
	v_cndmask_b32_e32 v18, 0, v19, vcc
	v_mul_f32_e32 v9, v9, v18
	v_mul_f32_e32 v8, v8, v18
	v_mul_f32_e32 v10, v10, v18
	v_mul_f32_e32 v11, v11, v18
	v_rndne_f32_e32 v9, v9
	v_rndne_f32_e32 v8, v8
	v_rndne_f32_e32 v10, v10
	v_rndne_f32_e32 v11, v11
	v_cvt_i32_f32_e32 v9, v9
	v_cvt_i32_f32_e32 v8, v8
	v_cvt_i32_f32_sdwa v10, v10 dst_sel:WORD_1 dst_unused:UNUSED_PAD src0_sel:DWORD
	v_cvt_i32_f32_e32 v11, v11
	v_lshlrev_b32_e32 v9, 8, v9
	v_and_b32_e32 v9, 0xff00, v9
	v_and_b32_e32 v10, 0xff0000, v10
	v_perm_b32 v8, v11, v8, s49
	v_or3_b32 v52, v8, v9, v10
	v_mul_f32_e32 v9, v21, v18
	v_mul_f32_e32 v19, v20, v18
	v_rndne_f32_e32 v9, v9
	v_mul_f32_e32 v6, v6, v18
	v_mul_f32_e32 v7, v7, v18
	v_rndne_f32_e32 v8, v19
	v_cvt_i32_f32_e32 v9, v9
	v_rndne_f32_e32 v6, v6
	v_rndne_f32_e32 v7, v7
	v_cvt_i32_f32_e32 v8, v8
	v_cvt_i32_f32_sdwa v6, v6 dst_sel:WORD_1 dst_unused:UNUSED_PAD src0_sel:DWORD
	v_cvt_i32_f32_e32 v7, v7
	v_lshlrev_b32_e32 v9, 8, v9
	v_and_b32_e32 v9, 0xff00, v9
	v_and_b32_e32 v6, 0xff0000, v6
	v_perm_b32 v7, v7, v8, s49
	v_or3_b32 v58, v7, v9, v6
	v_mul_f32_e32 v7, v17, v18
	v_mul_f32_e32 v6, v16, v18
	v_rndne_f32_e32 v7, v7
	v_mul_f32_e32 v2, v2, v18
	v_mul_f32_e32 v3, v3, v18
	v_rndne_f32_e32 v6, v6
	v_cvt_i32_f32_e32 v7, v7
	v_rndne_f32_e32 v2, v2
	v_rndne_f32_e32 v3, v3
	v_cvt_i32_f32_e32 v6, v6
	v_cvt_i32_f32_sdwa v2, v2 dst_sel:WORD_1 dst_unused:UNUSED_PAD src0_sel:DWORD
	v_cvt_i32_f32_e32 v3, v3
	v_lshlrev_b32_e32 v7, 8, v7
	v_and_b32_e32 v7, 0xff00, v7
	v_and_b32_e32 v2, 0xff0000, v2
	v_perm_b32 v3, v3, v6, s49
	v_cmp_gt_u32_e32 vcc, s50, v4
	v_or3_b32 v53, v3, v7, v2
	v_and_b32_e32 v8, s10, v74
	v_and_b32_e32 v7, vcc_lo, v74
	v_and_b32_e32 v6, vcc_hi, v65
	v_bcnt_u32_b32 v7, v7, 0
	v_ashrrev_i32_e32 v3, 11, v4
	v_bcnt_u32_b32 v6, v6, v7
	v_and_b32_e32 v7, s11, v65
	v_bcnt_u32_b32 v8, v8, 0
	v_cndmask_b32_e32 v6, 0, v6, vcc
	s_bcnt1_i32_b64 s34, vcc
	v_bcnt_u32_b32 v7, v7, v8
	v_cmp_eq_u32_e32 vcc, 1, v3
	v_add_u32_e32 v7, s34, v7
	v_ashrrev_i32_e32 v2, 11, v5
	v_and_b32_e32 v9, vcc_lo, v74
	v_cndmask_b32_e64 v7, 0, v7, s[10:11]
	s_bcnt1_i32_b64 s10, s[10:11]
	v_and_b32_e32 v8, vcc_hi, v65
	v_bcnt_u32_b32 v9, v9, 0
	s_add_i32 s34, s10, s34
	v_cmp_eq_u32_e64 s[10:11], 1, v2
	v_bcnt_u32_b32 v8, v8, v9
	v_add_u32_e32 v8, s34, v8
	v_and_b32_e32 v9, s10, v74
	v_cndmask_b32_e32 v6, v6, v8, vcc
	s_bcnt1_i32_b64 s35, vcc
	v_and_b32_e32 v8, s11, v65
	v_bcnt_u32_b32 v9, v9, 0
	s_add_i32 s34, s34, s35
	v_bcnt_u32_b32 v8, v8, v9
	v_cmp_eq_u32_e32 vcc, 2, v3
	v_add_u32_e32 v8, s34, v8
	v_cndmask_b32_e64 v7, v7, v8, s[10:11]
	v_and_b32_e32 v9, vcc_lo, v74
	s_bcnt1_i32_b64 s10, s[10:11]
	v_and_b32_e32 v8, vcc_hi, v65
	v_bcnt_u32_b32 v9, v9, 0
	s_add_i32 s34, s34, s10
	v_cmp_eq_u32_e64 s[10:11], 2, v2
	v_bcnt_u32_b32 v8, v8, v9
	v_add_u32_e32 v8, s34, v8
	v_and_b32_e32 v9, s10, v74
	v_cndmask_b32_e32 v6, v6, v8, vcc
	s_bcnt1_i32_b64 s35, vcc
	v_and_b32_e32 v8, s11, v65
	v_bcnt_u32_b32 v9, v9, 0
	s_add_i32 s34, s34, s35
	v_bcnt_u32_b32 v8, v8, v9
	v_cmp_eq_u32_e32 vcc, 3, v3
	v_add_u32_e32 v8, s34, v8
	v_cndmask_b32_e64 v7, v7, v8, s[10:11]
	v_and_b32_e32 v9, vcc_lo, v74
	s_bcnt1_i32_b64 s10, s[10:11]
	v_and_b32_e32 v8, vcc_hi, v65
	v_bcnt_u32_b32 v9, v9, 0
	s_add_i32 s34, s34, s10
	v_cmp_eq_u32_e64 s[10:11], 3, v2
	v_bcnt_u32_b32 v8, v8, v9
	v_add_u32_e32 v8, s34, v8
	v_and_b32_e32 v9, s10, v74
	v_cndmask_b32_e32 v6, v6, v8, vcc
	s_bcnt1_i32_b64 s35, vcc
	v_and_b32_e32 v8, s11, v65
	v_bcnt_u32_b32 v9, v9, 0
	s_add_i32 s34, s34, s35
	v_bcnt_u32_b32 v8, v8, v9
	v_cmp_eq_u32_e32 vcc, 4, v3
	v_add_u32_e32 v8, s34, v8
	v_cndmask_b32_e64 v7, v7, v8, s[10:11]
	v_and_b32_e32 v9, vcc_lo, v74
	s_bcnt1_i32_b64 s10, s[10:11]
	v_and_b32_e32 v8, vcc_hi, v65
	v_bcnt_u32_b32 v9, v9, 0
	s_add_i32 s34, s34, s10
	v_cmp_eq_u32_e64 s[10:11], 4, v2
	v_bcnt_u32_b32 v8, v8, v9
	v_add_u32_e32 v8, s34, v8
	v_and_b32_e32 v9, s10, v74
	v_cndmask_b32_e32 v6, v6, v8, vcc
	s_bcnt1_i32_b64 s35, vcc
	v_and_b32_e32 v8, s11, v65
	v_bcnt_u32_b32 v9, v9, 0
	s_add_i32 s34, s34, s35
	v_bcnt_u32_b32 v8, v8, v9
	v_cmp_eq_u32_e32 vcc, 5, v3
	v_add_u32_e32 v8, s34, v8
	v_cndmask_b32_e64 v7, v7, v8, s[10:11]
	v_and_b32_e32 v9, vcc_lo, v74
	s_bcnt1_i32_b64 s10, s[10:11]
	v_and_b32_e32 v8, vcc_hi, v65
	v_bcnt_u32_b32 v9, v9, 0
	s_add_i32 s34, s34, s10
	v_cmp_eq_u32_e64 s[10:11], 5, v2
	v_bcnt_u32_b32 v8, v8, v9
	v_add_u32_e32 v8, s34, v8
	v_and_b32_e32 v9, s10, v74
	v_cndmask_b32_e32 v6, v6, v8, vcc
	s_bcnt1_i32_b64 s35, vcc
	v_and_b32_e32 v8, s11, v65
	v_bcnt_u32_b32 v9, v9, 0
	s_add_i32 s34, s34, s35
	v_bcnt_u32_b32 v8, v8, v9
	v_cmp_eq_u32_e32 vcc, 6, v3
	v_add_u32_e32 v8, s34, v8
	v_cndmask_b32_e64 v7, v7, v8, s[10:11]
	v_and_b32_e32 v9, vcc_lo, v74
	s_bcnt1_i32_b64 s10, s[10:11]
	v_and_b32_e32 v8, vcc_hi, v65
	v_bcnt_u32_b32 v9, v9, 0
	s_add_i32 s34, s34, s10
	v_cmp_eq_u32_e64 s[10:11], 6, v2
	v_bcnt_u32_b32 v8, v8, v9
	v_add_u32_e32 v8, s34, v8
	v_and_b32_e32 v9, s10, v74
	v_cndmask_b32_e32 v6, v6, v8, vcc
	s_bcnt1_i32_b64 s35, vcc
	v_and_b32_e32 v8, s11, v65
	v_bcnt_u32_b32 v9, v9, 0
	s_add_i32 s34, s34, s35
	v_bcnt_u32_b32 v8, v8, v9
	v_add_u32_e32 v8, s34, v8
	v_cndmask_b32_e64 v7, v7, v8, s[10:11]
	s_bcnt1_i32_b64 s10, s[10:11]
	s_add_i32 s34, s34, s10
	v_cmp_eq_u32_e64 s[10:11], 7, v3
	v_cmp_eq_u32_e32 vcc, 7, v2
	v_mul_f32_e32 v13, v13, v18
	v_and_b32_e32 v3, s10, v74
	v_and_b32_e32 v2, s11, v65
	v_bcnt_u32_b32 v3, v3, 0
	v_bcnt_u32_b32 v2, v2, v3
	v_add_u32_e32 v2, s34, v2
	v_mul_f32_e32 v12, v12, v18
	v_mul_f32_e32 v14, v14, v18
	v_mul_f32_e32 v15, v15, v18
	v_rndne_f32_e32 v13, v13
	v_cndmask_b32_e64 v2, v6, v2, s[10:11]
	v_and_b32_e32 v6, vcc_lo, v74
	v_rndne_f32_e32 v12, v12
	v_rndne_f32_e32 v14, v14
	v_rndne_f32_e32 v15, v15
	v_cvt_i32_f32_e32 v13, v13
	s_bcnt1_i32_b64 s10, s[10:11]
	v_and_b32_e32 v3, vcc_hi, v65
	v_bcnt_u32_b32 v6, v6, 0
	v_cvt_i32_f32_e32 v12, v12
	v_cvt_i32_f32_sdwa v14, v14 dst_sel:WORD_1 dst_unused:UNUSED_PAD src0_sel:DWORD
	v_cvt_i32_f32_e32 v15, v15
	s_add_i32 s34, s34, s10
	v_bcnt_u32_b32 v3, v3, v6
	v_add_u32_e32 v3, s34, v3
	v_cndmask_b32_e32 v3, v7, v3, vcc
	v_lshlrev_b32_e32 v2, 1, v2
	v_lshlrev_b32_e32 v13, 8, v13
	v_add_u32_e32 v6, s39, v2
	v_lshlrev_b32_e32 v3, 1, v3
	v_and_b32_e32 v14, 0xff0000, v14
	v_perm_b32 v12, v15, v12, s49
	v_and_b32_e32 v11, 0xff00, v13
	ds_write_b16 v6, v4 offset:256
	v_add_u32_e32 v4, s39, v3
	v_add_u32_e32 v2, v6, v2
	v_or3_b32 v57, v12, v11, v14
	ds_write_b32 v2, v0 offset:1536
	v_add_u32_e32 v0, v4, v3
	ds_write_b16 v4, v5 offset:256
	ds_write_b32 v0, v1 offset:1536

; __device__ __forceinline__ void phase10(const Args& a, LAS unsigned char* lds, int tid, int wave, int lane, int vcu, int G, int emask, bool probe) {
;     ...
;                 const int brow = R < NP ? 0 : 1 + (int)((R - NP) >> 3);
;                 const float* mrow = mod + (size_t)brow * 6144;
;                 float x1v[16];
; #pragma unroll
;                 for (int q = 0; q < 4; ++q) { const f32x4 t4 = *(const f32x4*)(X1 + R * DM + c0 + 4 * q);
; #pragma unroll
;                     for (int e = 0; e < 4; ++e) x1v[4 * q + e] = t4[e]; }
;                 float ss = 0.f;
; #pragma unroll
;                 for (int e = 0; e < 16; ++e) ss += x1v[e] * x1v[e];
;                 const float rstd = 1.0f / sqrtf(wave_sum(ss) * (1.f / DM) + EPS);
;                 float h2[16], am = 0.f;
; #pragma unroll
;                 for (int e = 0; e < 16; ++e) { const int c = c0 + e; h2[e] = x1v[e] * rstd * a.in[16][c] * (1.f + mrow[4096 + c]) + mrow[3072 + c]; am = fmaxf(am, fabsf(h2[e])); }
; #pragma unroll
;                 for (int o = 1; o < 64; o <<= 1) am = fmaxf(am, __shfl_xor(am, o));
;                 const float inv = am > 0.f ? 127.f / am : 0.f; sh[tk] = am * (1.f / 127.f);
; #pragma unroll
;                 for (int q = 0; q < 4; ++q) { unsigned pk = 0;
; #pragma unroll
;                     for (int e = 0; e < 4; ++e) pk |= ((unsigned)(int)rintf(h2[4 * q + e] * inv) & 0xffu) << (8 * e);
;                     hq[tk][q] = pk; }
;                 const int e0 = SEL_E[R * 128 + 2 * lane], e1 = SEL_E[R * 128 + 2 * lane + 1]; const float g0 = SEL_G[R * 128 + 2 * lane], g1 = SEL_G[R * 128 + 2 * lane + 1];
.LBB0_1696:
	s_lshl_b64 s[64:65], s[34:35], 12
	v_lshl_add_u64 v[0:1], v[72:73], 0, s[64:65]
	s_waitcnt lgkmcnt(10)
	global_load_dwordx4 v[20:23], v[0:1], off
	s_waitcnt lgkmcnt(4)
	global_load_dwordx4 v[24:27], v[0:1], off offset:16
	global_load_dwordx4 v[28:31], v[0:1], off offset:32
	global_load_dwordx4 v[16:19], v[0:1], off offset:48
	v_lshl_add_u64 v[0:1], s[10:11], 2, v[86:87]
	v_add_co_u32_e32 v2, vcc, s46, v0
	v_lshl_add_u64 v[8:9], v[0:1], 0, s[28:29]
	s_nop 0
	v_addc_co_u32_e32 v3, vcc, 0, v1, vcc
	global_load_dwordx4 v[32:35], v[2:3], off
	v_lshl_add_u64 v[2:3], v[0:1], 0, s[26:27]
	global_load_dwordx4 v[36:39], v[2:3], off offset:16
	global_load_dwordx4 v[40:43], v[2:3], off offset:32
	global_load_dwordx4 v[44:47], v[2:3], off offset:48
	global_load_dwordx4 v[60:63], v[82:83], off offset:48
	global_load_dwordx4 v[94:97], v[82:83], off offset:32
	s_waitcnt lgkmcnt(6)
	global_load_dwordx4 v[98:101], v[82:83], off offset:16
	s_waitcnt lgkmcnt(2)
	global_load_dwordx4 v[102:105], v[82:83], off
	v_add_co_u32_e32 v122, vcc, s47, v0
	s_nop 1
	v_addc_co_u32_e32 v123, vcc, 0, v1, vcc
	global_load_dwordx4 v[124:127], v[122:123], off
	global_load_dwordx4 v[128:131], v[8:9], off offset:48
	global_load_dwordx4 v[132:135], v[8:9], off offset:32
	global_load_dwordx4 v[136:139], v[8:9], off offset:16
	s_lshl_b64 s[66:67], s[34:35], 9
	v_lshl_or_b32 v140, v66, 2, s66
	v_mov_b32_e32 v141, s67
	v_lshl_add_u64 v[142:143], s[20:21], 0, v[140:141]
	v_lshl_add_u64 v[140:141], s[22:23], 0, v[140:141]
	global_load_dwordx2 v[144:145], v[140:141], off
	global_load_dwordx2 v[146:147], v[142:143], off
	v_add_co_u32_e32 v0, vcc, s47, v0
	s_waitcnt vmcnt(17)
	v_mul_f32_e32 v2, v21, v21
	v_fmac_f32_e32 v2, v20, v20
	v_fmac_f32_e32 v2, v22, v22
	v_fmac_f32_e32 v2, v23, v23
	s_waitcnt vmcnt(16)
	v_fmac_f32_e32 v2, v24, v24
	v_fmac_f32_e32 v2, v25, v25
	v_fmac_f32_e32 v2, v26, v26
	v_fmac_f32_e32 v2, v27, v27
	s_waitcnt vmcnt(15)
	v_fmac_f32_e32 v2, v28, v28
	v_fmac_f32_e32 v2, v29, v29
	v_fmac_f32_e32 v2, v30, v30
	v_fmac_f32_e32 v2, v31, v31
	s_waitcnt vmcnt(14)
	v_fmac_f32_e32 v2, v16, v16
	v_fmac_f32_e32 v2, v17, v17
	v_fmac_f32_e32 v2, v18, v18
	v_fmac_f32_e32 v2, v19, v19
	ds_bpermute_b32 v3, v217, v2
	v_addc_co_u32_e32 v1, vcc, 0, v1, vcc
	s_waitcnt vmcnt(13)
	v_add_f32_e32 v32, 1.0, v32
	v_add_f32_e32 v33, 1.0, v33
	s_waitcnt lgkmcnt(0)
	v_add_f32_e32 v2, v2, v3
	ds_bpermute_b32 v3, v218, v2
	v_add_f32_e32 v34, 1.0, v34
	v_add_f32_e32 v35, 1.0, v35
	s_waitcnt vmcnt(10)
	v_add_f32_e32 v44, 1.0, v44
	v_add_f32_e32 v36, 1.0, v36
	s_waitcnt lgkmcnt(0)
	v_add_f32_e32 v56, v2, v3
	s_waitcnt vmcnt(2)
	v_mov_b64_e32 v[12:13], v[124:125]
	v_mov_b64_e32 v[14:15], v[126:127]
	s_nop 0
	v_mov_b64_e32 v[0:1], v[128:129]
	v_mov_b64_e32 v[2:3], v[130:131]
	v_mov_b64_e32 v[4:5], v[132:133]
	v_mov_b64_e32 v[6:7], v[134:135]
	s_nop 0
	v_mov_b64_e32 v[8:9], v[136:137]
	v_mov_b64_e32 v[10:11], v[138:139]
	ds_bpermute_b32 v59, v219, v56
	v_add_f32_e32 v37, 1.0, v37
	v_add_f32_e32 v38, 1.0, v38
	v_add_f32_e32 v39, 1.0, v39
	v_add_f32_e32 v40, 1.0, v40
	s_waitcnt lgkmcnt(0)
	v_add_f32_e32 v56, v56, v59
	ds_bpermute_b32 v59, v220, v56
	v_add_f32_e32 v41, 1.0, v41
	v_add_f32_e32 v42, 1.0, v42
	v_add_f32_e32 v43, 1.0, v43
	v_add_f32_e32 v45, 1.0, v45
	s_waitcnt lgkmcnt(0)
	v_add_f32_e32 v56, v56, v59
	ds_bpermute_b32 v59, v215, v56
	v_add_f32_e32 v46, 1.0, v46
	v_add_f32_e32 v47, 1.0, v47
	s_waitcnt lgkmcnt(0)
	v_add_f32_e32 v56, v56, v59
	ds_bpermute_b32 v59, v216, v56
	s_waitcnt lgkmcnt(0)
	v_add_f32_e32 v56, v56, v59
	v_fmamk_f32 v56, v56, 0x3a800000, v227
	v_mul_f32_e32 v59, 0x4f800000, v56
	v_cmp_gt_f32_e32 vcc, s45, v56
	s_nop 1
	v_cndmask_b32_e32 v56, v56, v59, vcc
	v_sqrt_f32_e32 v59, v56
	s_nop 0
	v_add_u32_e32 v68, -1, v59
	v_add_u32_e32 v106, 1, v59
	v_fma_f32 v107, -v68, v59, v56
	v_fma_f32 v108, -v106, v59, v56
	v_cmp_ge_f32_e64 s[10:11], 0, v107
	s_nop 1
	v_cndmask_b32_e64 v59, v59, v68, s[10:11]
	v_cmp_lt_f32_e64 s[10:11], 0, v108
	s_nop 1
	v_cndmask_b32_e64 v59, v59, v106, s[10:11]
	v_mul_f32_e32 v68, 0x37800000, v59
	v_cndmask_b32_e32 v59, v59, v68, vcc
	v_cmp_class_f32_e32 vcc, v56, v228
	s_nop 1
	v_cndmask_b32_e32 v56, v59, v56, vcc
	v_div_scale_f32 v59, s[10:11], v56, v56, 1.0
	v_rcp_f32_e32 v68, v59
	v_div_scale_f32 v106, vcc, 1.0, v56, 1.0
	s_lshl_b64 s[10:11], s[34:35], 9
	v_fma_f32 v107, -v59, v68, 1.0
	v_fmac_f32_e32 v68, v107, v68
	v_mul_f32_e32 v107, v106, v68
	v_fma_f32 v108, -v59, v107, v106
	v_fmac_f32_e32 v107, v108, v68
	v_fma_f32 v59, -v59, v107, v106
	v_div_fmas_f32 v59, v59, v68, v107
	v_div_fixup_f32 v56, v59, v56, 1.0
	v_mul_f32_e32 v20, v20, v56
	v_mul_f32_e32 v21, v21, v56
	v_mul_f32_e32 v22, v22, v56
	v_mul_f32_e32 v23, v23, v56
	v_mul_f32_e32 v16, v16, v56
	s_waitcnt vmcnt(4)
	v_mul_f32_e32 v20, v102, v20
	v_mul_f32_e32 v21, v103, v21
	v_mul_f32_e32 v24, v24, v56
	v_mul_f32_e32 v25, v25, v56
	v_mul_f32_e32 v22, v104, v22
	v_mul_f32_e32 v23, v105, v23
	v_mul_f32_e32 v16, v16, v60
	s_waitcnt vmcnt(3)
	v_fma_f32 v12, v32, v20, v12
	v_fma_f32 v13, v33, v21, v13
	v_mul_f32_e32 v26, v26, v56
	v_mul_f32_e32 v27, v27, v56
	v_mul_f32_e32 v24, v98, v24
	v_mul_f32_e32 v25, v99, v25
	v_fma_f32 v14, v34, v22, v14
	v_fmac_f32_e32 v15, v35, v23
	s_waitcnt vmcnt(2)
	v_fma_f32 v16, v16, v44, v0
	v_max3_f32 v0, |v12|, 0, |v13|
	v_mul_f32_e32 v28, v28, v56
	v_mul_f32_e32 v29, v29, v56
	v_mul_f32_e32 v26, v26, v100
	v_mul_f32_e32 v27, v27, v101
	s_waitcnt vmcnt(0)
; __device__ __forceinline__ void phase10(const Args& a, LAS unsigned char* lds, int tid, int wave, int lane, int vcu, int G, int emask, bool probe) {
;     ...
;                 float h2[16], am = 0.f;
; #pragma unroll
;                 for (int e = 0; e < 16; ++e) { const int c = c0 + e; h2[e] = x1v[e] * rstd * a.in[16][c] * (1.f + mrow[4096 + c]) + mrow[3072 + c]; am = fmaxf(am, fabsf(h2[e])); }
; #pragma unroll
;                 for (int o = 1; o < 64; o <<= 1) am = fmaxf(am, __shfl_xor(am, o));
;                 const float inv = am > 0.f ? 127.f / am : 0.f; sh[tk] = am * (1.f / 127.f);
; #pragma unroll
;                 for (int q = 0; q < 4; ++q) { unsigned pk = 0;
; #pragma unroll
;                     for (int e = 0; e < 4; ++e) pk |= ((unsigned)(int)rintf(h2[4 * q + e] * inv) & 0xffu) << (8 * e);
;                     hq[tk][q] = pk; }
;                 const int e0 = SEL_E[R * 128 + 2 * lane], e1 = SEL_E[R * 128 + 2 * lane + 1]; const float g0 = SEL_G[R * 128 + 2 * lane], g1 = SEL_G[R * 128 + 2 * lane + 1];
	v_fma_f32 v8, v36, v24, v8
	v_fma_f32 v9, v37, v25, v9
	v_max3_f32 v0, v0, |v14|, |v15|
	v_mul_f32_e32 v30, v30, v56
	v_mul_f32_e32 v31, v31, v56
	v_mul_f32_e32 v28, v28, v94
	v_mul_f32_e32 v29, v29, v95
	v_fma_f32 v10, v26, v38, v10
	v_fmac_f32_e32 v11, v27, v39
	v_max3_f32 v0, v0, |v8|, |v9|
	v_mul_f32_e32 v17, v17, v56
	v_mul_f32_e32 v30, v30, v96
	v_mul_f32_e32 v31, v31, v97
	v_fma_f32 v20, v28, v40, v4
	v_fma_f32 v21, v29, v41, v5
	v_max3_f32 v0, v0, |v10|, |v11|
	v_mul_f32_e32 v18, v18, v56
	v_mul_f32_e32 v19, v19, v56
	v_mul_f32_e32 v17, v17, v61
	v_fma_f32 v6, v30, v42, v6
	v_fmac_f32_e32 v7, v31, v43
	v_max3_f32 v0, v0, |v20|, |v21|
	v_mul_f32_e32 v18, v18, v62
	v_mul_f32_e32 v19, v19, v63
	v_fma_f32 v17, v17, v45, v1
	v_max3_f32 v0, v0, |v6|, |v7|
	v_fma_f32 v2, v18, v46, v2
	v_fmac_f32_e32 v3, v19, v47
	v_max3_f32 v0, v0, |v16|, |v17|
	v_max3_f32 v0, v0, |v2|, |v3|
	ds_bpermute_b32 v1, v217, v0
	s_waitcnt lgkmcnt(0)
	v_max_f32_e32 v1, v1, v1
	v_max_f32_e32 v0, v0, v1
	ds_bpermute_b32 v1, v218, v0
	s_waitcnt lgkmcnt(0)
	v_max_f32_e32 v1, v1, v1
	v_max_f32_e32 v0, v0, v1
	ds_bpermute_b32 v1, v219, v0
	s_waitcnt lgkmcnt(0)
	v_max_f32_e32 v1, v1, v1
	v_max_f32_e32 v0, v0, v1
	ds_bpermute_b32 v1, v220, v0
	s_waitcnt lgkmcnt(0)
	v_max_f32_e32 v1, v1, v1
	v_max_f32_e32 v4, v0, v1
	ds_bpermute_b32 v5, v215, v4
	v_lshl_or_b32 v0, v66, 2, s10
	v_mov_b32_e32 v1, s11
	s_waitcnt lgkmcnt(0)
	v_max_f32_e32 v5, v5, v5
	v_max_f32_e32 v18, v4, v5
	v_lshl_add_u64 v[4:5], s[20:21], 0, v[0:1]
	v_lshl_add_u64 v[0:1], s[22:23], 0, v[0:1]
	s_waitcnt vmcnt(0)
	v_mov_b64_e32 v[0:1], v[144:145]
	s_nop 0
	v_mov_b64_e32 v[4:5], v[146:147]
	ds_bpermute_b32 v19, v216, v18
	s_waitcnt lgkmcnt(0)
	v_max_f32_e32 v19, v19, v19
	v_max_f32_e32 v18, v18, v19
	v_div_scale_f32 v19, s[10:11], v18, v18, s48
	v_rcp_f32_e32 v22, v19
	v_div_scale_f32 v23, vcc, s48, v18, s48
	v_mul_f32_e32 v56, 0x3c010204, v18
	v_fma_f32 v24, -v19, v22, 1.0
	v_fmac_f32_e32 v22, v24, v22
	v_mul_f32_e32 v24, v23, v22
	v_fma_f32 v25, -v19, v24, v23
	v_fmac_f32_e32 v24, v25, v22
	v_fma_f32 v19, -v19, v24, v23
	v_div_fmas_f32 v19, v19, v22, v24
	v_div_fixup_f32 v19, v19, v18, s48
	v_cmp_lt_f32_e32 vcc, 0, v18
	s_waitcnt vmcnt(0)
; __device__ __forceinline__ void phase10(const Args& a, LAS unsigned char* lds, int tid, int wave, int lane, int vcu, int G, int emask, bool probe) {
;     ...
;                 const float inv = am > 0.f ? 127.f / am : 0.f; sh[tk] = am * (1.f / 127.f);
; #pragma unroll
;                 for (int q = 0; q < 4; ++q) { unsigned pk = 0;
; #pragma unroll
;                     for (int e = 0; e < 4; ++e) pk |= ((unsigned)(int)rintf(h2[4 * q + e] * inv) & 0xffu) << (8 * e);
;                     hq[tk][q] = pk; }
;                 const int e0 = SEL_E[R * 128 + 2 * lane], e1 = SEL_E[R * 128 + 2 * lane + 1]; const float g0 = SEL_G[R * 128 + 2 * lane], g1 = SEL_G[R * 128 + 2 * lane + 1];
;                 const int r0 = e0 >> 11, r1 = e1 >> 11; int pos0 = 0, pos1 = 0, off = 0;
;                 const unsigned long long lt = (1ull << lane) - 1ull;
;                 for (int r = 0; r < NRANGE; ++r) {
;                     const unsigned long long m0 = __ballot(r0 == r), m1 = __ballot(r1 == r);
;                     if (r0 == r) pos0 = off + __popcll(m0 & lt);
;                     if (r1 == r) pos1 = off + __popcll(m0) + __popcll(m1 & lt);
;                     off += __popcll(m0) + __popcll(m1);
;                 }
;                 PE[tk * 128 + pos0] = (unsigned short)e0; PE[tk * 128 + pos1] = (unsigned short)e1; PG[tk * 128 + pos0] = g0; PG[tk * 128 + pos1] = g1;
	v_cmp_gt_u32_e64 s[10:11], s50, v5
	v_cndmask_b32_e32 v18, 0, v19, vcc
	v_mul_f32_e32 v9, v9, v18
	v_mul_f32_e32 v8, v8, v18
	v_mul_f32_e32 v10, v10, v18
	v_mul_f32_e32 v11, v11, v18
	v_rndne_f32_e32 v9, v9
	v_rndne_f32_e32 v8, v8
	v_rndne_f32_e32 v10, v10
	v_rndne_f32_e32 v11, v11
	v_cvt_i32_f32_e32 v9, v9
	v_cvt_i32_f32_e32 v8, v8
	v_cvt_i32_f32_sdwa v10, v10 dst_sel:WORD_1 dst_unused:UNUSED_PAD src0_sel:DWORD
	v_cvt_i32_f32_e32 v11, v11
	v_lshlrev_b32_e32 v9, 8, v9
	v_and_b32_e32 v9, 0xff00, v9
	v_and_b32_e32 v10, 0xff0000, v10
	v_perm_b32 v8, v11, v8, s49
	v_or3_b32 v63, v8, v9, v10
	v_mul_f32_e32 v9, v21, v18
	v_mul_f32_e32 v19, v20, v18
	v_rndne_f32_e32 v9, v9
	v_mul_f32_e32 v6, v6, v18
	v_mul_f32_e32 v7, v7, v18
	v_rndne_f32_e32 v8, v19
	v_cvt_i32_f32_e32 v9, v9
	v_rndne_f32_e32 v6, v6
	v_rndne_f32_e32 v7, v7
	v_cvt_i32_f32_e32 v8, v8
	v_cvt_i32_f32_sdwa v6, v6 dst_sel:WORD_1 dst_unused:UNUSED_PAD src0_sel:DWORD
	v_cvt_i32_f32_e32 v7, v7
	v_lshlrev_b32_e32 v9, 8, v9
	v_and_b32_e32 v9, 0xff00, v9
	v_and_b32_e32 v6, 0xff0000, v6
	v_perm_b32 v7, v7, v8, s49
	v_or3_b32 v95, v7, v9, v6
	v_mul_f32_e32 v7, v17, v18
	v_mul_f32_e32 v6, v16, v18
	v_rndne_f32_e32 v7, v7
	v_mul_f32_e32 v2, v2, v18
	v_mul_f32_e32 v3, v3, v18
	v_rndne_f32_e32 v6, v6
	v_cvt_i32_f32_e32 v7, v7
	v_rndne_f32_e32 v2, v2
	v_rndne_f32_e32 v3, v3
	v_cvt_i32_f32_e32 v6, v6
	v_cvt_i32_f32_sdwa v2, v2 dst_sel:WORD_1 dst_unused:UNUSED_PAD src0_sel:DWORD
	v_cvt_i32_f32_e32 v3, v3
	v_lshlrev_b32_e32 v7, 8, v7
	v_and_b32_e32 v7, 0xff00, v7
	v_and_b32_e32 v2, 0xff0000, v2
	v_perm_b32 v3, v3, v6, s49
	v_cmp_gt_u32_e32 vcc, s50, v4
	v_or3_b32 v99, v3, v7, v2
	v_and_b32_e32 v8, s10, v74
	v_and_b32_e32 v7, vcc_lo, v74
	v_and_b32_e32 v6, vcc_hi, v65
	v_bcnt_u32_b32 v7, v7, 0
	v_ashrrev_i32_e32 v3, 11, v4
	v_bcnt_u32_b32 v6, v6, v7
	v_and_b32_e32 v7, s11, v65
	v_bcnt_u32_b32 v8, v8, 0
	v_cndmask_b32_e32 v6, 0, v6, vcc
	s_bcnt1_i32_b64 s34, vcc
	v_bcnt_u32_b32 v7, v7, v8
	v_cmp_eq_u32_e32 vcc, 1, v3
	v_add_u32_e32 v7, s34, v7
	v_ashrrev_i32_e32 v2, 11, v5
	v_and_b32_e32 v9, vcc_lo, v74
	v_cndmask_b32_e64 v7, 0, v7, s[10:11]
	s_bcnt1_i32_b64 s10, s[10:11]
	v_and_b32_e32 v8, vcc_hi, v65
	v_bcnt_u32_b32 v9, v9, 0
	s_add_i32 s34, s10, s34
	v_cmp_eq_u32_e64 s[10:11], 1, v2
	v_bcnt_u32_b32 v8, v8, v9
	v_add_u32_e32 v8, s34, v8
	v_and_b32_e32 v9, s10, v74
	v_cndmask_b32_e32 v6, v6, v8, vcc
	s_bcnt1_i32_b64 s35, vcc
	v_and_b32_e32 v8, s11, v65
	v_bcnt_u32_b32 v9, v9, 0
	s_add_i32 s34, s34, s35
	v_bcnt_u32_b32 v8, v8, v9
	v_cmp_eq_u32_e32 vcc, 2, v3
	v_add_u32_e32 v8, s34, v8
	v_cndmask_b32_e64 v7, v7, v8, s[10:11]
	v_and_b32_e32 v9, vcc_lo, v74
	s_bcnt1_i32_b64 s10, s[10:11]
	v_and_b32_e32 v8, vcc_hi, v65
	v_bcnt_u32_b32 v9, v9, 0
	s_add_i32 s34, s34, s10
	v_cmp_eq_u32_e64 s[10:11], 2, v2
	v_bcnt_u32_b32 v8, v8, v9
	v_add_u32_e32 v8, s34, v8
	v_and_b32_e32 v9, s10, v74
	v_cndmask_b32_e32 v6, v6, v8, vcc
	s_bcnt1_i32_b64 s35, vcc
	v_and_b32_e32 v8, s11, v65
	v_bcnt_u32_b32 v9, v9, 0
	s_add_i32 s34, s34, s35
	v_bcnt_u32_b32 v8, v8, v9
	v_cmp_eq_u32_e32 vcc, 3, v3
	v_add_u32_e32 v8, s34, v8
	v_cndmask_b32_e64 v7, v7, v8, s[10:11]
	v_and_b32_e32 v9, vcc_lo, v74
	s_bcnt1_i32_b64 s10, s[10:11]
	v_and_b32_e32 v8, vcc_hi, v65
	v_bcnt_u32_b32 v9, v9, 0
	s_add_i32 s34, s34, s10
	v_cmp_eq_u32_e64 s[10:11], 3, v2
	v_bcnt_u32_b32 v8, v8, v9
	v_add_u32_e32 v8, s34, v8
	v_and_b32_e32 v9, s10, v74
	v_cndmask_b32_e32 v6, v6, v8, vcc
	s_bcnt1_i32_b64 s35, vcc
	v_and_b32_e32 v8, s11, v65
	v_bcnt_u32_b32 v9, v9, 0
	s_add_i32 s34, s34, s35
	v_bcnt_u32_b32 v8, v8, v9
	v_cmp_eq_u32_e32 vcc, 4, v3
	v_add_u32_e32 v8, s34, v8
	v_cndmask_b32_e64 v7, v7, v8, s[10:11]
	v_and_b32_e32 v9, vcc_lo, v74
	s_bcnt1_i32_b64 s10, s[10:11]
	v_and_b32_e32 v8, vcc_hi, v65
	v_bcnt_u32_b32 v9, v9, 0
	s_add_i32 s34, s34, s10
	v_cmp_eq_u32_e64 s[10:11], 4, v2
	v_bcnt_u32_b32 v8, v8, v9
	v_add_u32_e32 v8, s34, v8
	v_and_b32_e32 v9, s10, v74
	v_cndmask_b32_e32 v6, v6, v8, vcc
	s_bcnt1_i32_b64 s35, vcc
	v_and_b32_e32 v8, s11, v65
	v_bcnt_u32_b32 v9, v9, 0
	s_add_i32 s34, s34, s35
	v_bcnt_u32_b32 v8, v8, v9
	v_cmp_eq_u32_e32 vcc, 5, v3
	v_add_u32_e32 v8, s34, v8
	v_cndmask_b32_e64 v7, v7, v8, s[10:11]
	v_and_b32_e32 v9, vcc_lo, v74
	s_bcnt1_i32_b64 s10, s[10:11]
	v_and_b32_e32 v8, vcc_hi, v65
	v_bcnt_u32_b32 v9, v9, 0
	s_add_i32 s34, s34, s10
	v_cmp_eq_u32_e64 s[10:11], 5, v2
	v_bcnt_u32_b32 v8, v8, v9
	v_add_u32_e32 v8, s34, v8
	v_and_b32_e32 v9, s10, v74
	v_cndmask_b32_e32 v6, v6, v8, vcc
	s_bcnt1_i32_b64 s35, vcc
	v_and_b32_e32 v8, s11, v65
	v_bcnt_u32_b32 v9, v9, 0
	s_add_i32 s34, s34, s35
	v_bcnt_u32_b32 v8, v8, v9
	v_cmp_eq_u32_e32 vcc, 6, v3
	v_add_u32_e32 v8, s34, v8
	v_cndmask_b32_e64 v7, v7, v8, s[10:11]
	v_and_b32_e32 v9, vcc_lo, v74
	s_bcnt1_i32_b64 s10, s[10:11]
	v_and_b32_e32 v8, vcc_hi, v65
	v_bcnt_u32_b32 v9, v9, 0
	s_add_i32 s34, s34, s10
	v_cmp_eq_u32_e64 s[10:11], 6, v2
	v_bcnt_u32_b32 v8, v8, v9
	v_add_u32_e32 v8, s34, v8
	v_and_b32_e32 v9, s10, v74
	v_cndmask_b32_e32 v6, v6, v8, vcc
	s_bcnt1_i32_b64 s35, vcc
	v_and_b32_e32 v8, s11, v65
	v_bcnt_u32_b32 v9, v9, 0
	s_add_i32 s34, s34, s35
	v_bcnt_u32_b32 v8, v8, v9
	v_add_u32_e32 v8, s34, v8
	v_cndmask_b32_e64 v7, v7, v8, s[10:11]
	s_bcnt1_i32_b64 s10, s[10:11]
	s_add_i32 s34, s34, s10
	v_cmp_eq_u32_e64 s[10:11], 7, v3
	v_cmp_eq_u32_e32 vcc, 7, v2
	v_mul_f32_e32 v13, v13, v18
	v_and_b32_e32 v3, s10, v74
	v_and_b32_e32 v2, s11, v65
	v_bcnt_u32_b32 v3, v3, 0
	v_bcnt_u32_b32 v2, v2, v3
	v_add_u32_e32 v2, s34, v2
	v_mul_f32_e32 v12, v12, v18
	v_mul_f32_e32 v14, v14, v18
	v_mul_f32_e32 v15, v15, v18
	v_rndne_f32_e32 v13, v13
	v_cndmask_b32_e64 v2, v6, v2, s[10:11]
	v_and_b32_e32 v6, vcc_lo, v74
	v_rndne_f32_e32 v12, v12
	v_rndne_f32_e32 v14, v14
	v_rndne_f32_e32 v15, v15
	v_cvt_i32_f32_e32 v13, v13
	s_bcnt1_i32_b64 s10, s[10:11]
	v_and_b32_e32 v3, vcc_hi, v65
	v_bcnt_u32_b32 v6, v6, 0
	v_cvt_i32_f32_e32 v12, v12
	v_cvt_i32_f32_sdwa v14, v14 dst_sel:WORD_1 dst_unused:UNUSED_PAD src0_sel:DWORD
	v_cvt_i32_f32_e32 v15, v15
	s_add_i32 s34, s34, s10
	v_bcnt_u32_b32 v3, v3, v6
	v_add_u32_e32 v3, s34, v3
	v_cndmask_b32_e32 v3, v7, v3, vcc
	v_lshlrev_b32_e32 v2, 1, v2
	v_lshlrev_b32_e32 v13, 8, v13
	v_add_u32_e32 v6, s39, v2
	v_lshlrev_b32_e32 v3, 1, v3
	v_and_b32_e32 v14, 0xff0000, v14
	v_perm_b32 v12, v15, v12, s49
	v_and_b32_e32 v11, 0xff00, v13
	ds_write_b16 v6, v4 offset:512
	v_add_u32_e32 v4, s39, v3
	v_add_u32_e32 v2, v6, v2
	v_or3_b32 v94, v12, v11, v14
	ds_write_b32 v2, v0 offset:2048
	v_add_u32_e32 v0, v4, v3
	ds_write_b16 v4, v5 offset:512
	ds_write_b32 v0, v1 offset:2048

; #define LAS __attribute__((address_space(3)))
; __device__ __forceinline__ void phase10(const Args& a, LAS unsigned char* lds, int tid, int wave, int lane, int vcu, int G, int emask, bool probe) {
;     ...
; #pragma unroll
;         for (int tk = 0; tk < GTK; ++tk) {
; #pragma unroll
;             for (int q = 0; q < 4; ++q) { const f32x4 s4 = *(const LAS f32x4*)(YS + (tk * 32 + lq) * 16 + 4 * q);
; #pragma unroll
;                 for (int e = 0; e < 4; ++e) { const float s1 = y[tk][4 * q + e] + __shfl_xor(y[tk][4 * q + e], 32); y[tk][4 * q + e] = hl ? s1 : s4[e]; } } }
; #pragma unroll
;         for (int tk = 0; tk < GTK; ++tk) {
;             const int slot = GTK * rd + tk;
;             const size_t R = G == 256 ? ((slot < 8 || (slot == 8 && wave < 4)) ? (size_t)68 * vcu + (slot < 8 ? wave + 8 * slot : 64 + wave) : (size_t)MT) : (size_t)gw + (size_t)slot * NGW;
;             if (R < MT) {
;                 const int brow = R < NP ? 0 : 1 + (int)((R - NP) >> 3);
;                 const float* mrow = mod + (size_t)brow * 6144;
;                 float xo[16]; float s2 = 0.f;
; #pragma unroll
;                 for (int q = 0; q < 4; ++q) { const f32x4 t4 = *(const f32x4*)(X1 + R * DM + c0 + 4 * q), g4 = *(const f32x4*)(mrow + 5120 + c0 + 4 * q);
; #pragma unroll
;                     for (int e = 0; e < 4; ++e) { xo[4 * q + e] = t4[e] + g4[e] * y[tk][4 * q + e]; s2 += xo[4 * q + e] * xo[4 * q + e]; } }
;                 const float r2 = 1.0f / sqrtf(wave_sum(s2) * (1.f / DM) + EPS);
;                 float* dst = probe ? (float*)(ws + WS_QP) + R * DM : (R < NP ? a.out + O_YP + R * DM : a.out + O_YS + (R - NP) * DM);
; #pragma unroll
;                 for (int q = 0; q < 4; ++q) { const f32x4 gf = *(const f32x4*)(a.in[22] + c0 + 4 * q); f32x4 o;
; #pragma unroll
;                     for (int e = 0; e < 4; ++e) o[e] = xo[4 * q + e] * r2 * gf[e];
;                     *(f32x4*)(dst + c0 + 4 * q) = o; }
.LBB0_1772:
	s_lshl_b64 s[34:35], s[34:35], 2
	s_add_u32 s54, s18, s34
	s_addc_u32 s55, s19, s35
	v_lshlrev_b32_e32 v68, 2, v64
	s_lshl_b64 s[34:35], s[10:11], 12
	v_lshl_add_u64 v[14:15], s[54:55], 0, v[68:69]
	v_lshl_add_u64 v[10:11], v[72:73], 0, s[34:35]
	v_lshl_add_u64 v[94:95], v[14:15], 0, s[30:31]
	v_add_co_u32_e32 v14, vcc, s52, v14
	s_waitcnt lgkmcnt(14)
	global_load_dwordx4 v[48:51], v[10:11], off offset:48
	v_addc_co_u32_e32 v15, vcc, 0, v15, vcc
	global_load_dwordx4 v[52:55], v[14:15], off
	global_load_dwordx4 v[56:59], v[94:95], off offset:48
	global_load_dwordx4 v[60:63], v[10:11], off
	global_load_dwordx4 v[152:155], v[10:11], off offset:16
	global_load_dwordx4 v[156:159], v[94:95], off offset:16
	global_load_dwordx4 v[160:163], v[94:95], off offset:32
	global_load_dwordx4 v[164:167], v[10:11], off offset:32
	v_pk_add_f32 v[10:11], v[130:131], v[134:135]
	v_pk_add_f32 v[14:15], v[132:133], v[136:137]
	v_pk_add_f32 v[100:101], v[126:127], v[140:141]
	v_cndmask_b32_e64 v11, v11, v37, s[6:7]
	v_cndmask_b32_e64 v10, v10, v36, s[6:7]
	v_pk_add_f32 v[104:105], v[124:125], v[142:143]
	v_pk_add_f32 v[124:125], v[122:123], v[144:145]
	v_pk_add_f32 v[126:127], v[120:121], v[146:147]
	v_cndmask_b32_e64 v15, v15, v39, s[6:7]
	v_cndmask_b32_e64 v14, v14, v38, s[6:7]
	v_cndmask_b32_e64 v35, v101, v35, s[6:7]
	v_cndmask_b32_e64 v34, v100, v34, s[6:7]
	v_pk_add_f32 v[94:95], v[128:129], v[138:139]
	v_cndmask_b32_e64 v39, v125, v47, s[6:7]
	v_cndmask_b32_e64 v38, v124, v46, s[6:7]
	v_cndmask_b32_e64 v41, v127, v41, s[6:7]
	v_cndmask_b32_e64 v40, v126, v40, s[6:7]
	v_pk_add_f32 v[128:129], v[148:149], v[150:151]
	global_load_dwordx4 v[120:123], v[84:85], off
	global_load_dwordx4 v[168:171], v[84:85], off offset:16
	global_load_dwordx4 v[172:175], v[84:85], off offset:32
	global_load_dwordx4 v[176:179], v[84:85], off offset:48
	v_cndmask_b32_e64 v33, v95, v33, s[6:7]
	v_cndmask_b32_e64 v32, v94, v32, s[6:7]
	v_cndmask_b32_e64 v37, v105, v45, s[6:7]
	v_cndmask_b32_e64 v36, v104, v44, s[6:7]
	v_cndmask_b32_e64 v43, v129, v43, s[6:7]
	v_cndmask_b32_e64 v42, v128, v42, s[6:7]
	s_waitcnt vmcnt(8)
	v_pk_fma_f32 v[10:11], v[10:11], v[52:53], v[60:61]
	v_pk_fma_f32 v[14:15], v[14:15], v[54:55], v[62:63]
	s_waitcnt vmcnt(6)
	v_pk_fma_f32 v[46:47], v[34:35], v[158:159], v[154:155]
	v_pk_mul_f32 v[34:35], v[10:11], v[10:11]
	v_pk_fma_f32 v[40:41], v[40:41], v[56:57], v[48:49]
	v_pk_mul_f32 v[48:49], v[14:15], v[14:15]
	v_add_f32_e32 v34, v34, v35
	v_pk_fma_f32 v[44:45], v[32:33], v[156:157], v[152:153]
	v_add_f32_e32 v34, v48, v34
	v_pk_fma_f32 v[42:43], v[42:43], v[58:59], v[50:51]
	v_pk_mul_f32 v[50:51], v[44:45], v[44:45]
	v_add_f32_e32 v34, v49, v34
	v_add_f32_e32 v34, v50, v34
	v_pk_mul_f32 v[52:53], v[46:47], v[46:47]
	v_add_f32_e32 v34, v51, v34
	s_waitcnt vmcnt(4)
	v_pk_fma_f32 v[36:37], v[36:37], v[160:161], v[164:165]
	v_add_f32_e32 v34, v52, v34
	v_pk_mul_f32 v[54:55], v[36:37], v[36:37]
	v_add_f32_e32 v34, v53, v34
	v_pk_fma_f32 v[38:39], v[38:39], v[162:163], v[166:167]
	v_add_f32_e32 v34, v54, v34
	v_pk_mul_f32 v[56:57], v[38:39], v[38:39]
	v_add_f32_e32 v34, v55, v34
	v_add_f32_e32 v34, v56, v34
	v_pk_mul_f32 v[58:59], v[40:41], v[40:41]
	v_add_f32_e32 v34, v57, v34
	v_add_f32_e32 v34, v58, v34
	v_pk_mul_f32 v[32:33], v[42:43], v[42:43]
	v_add_f32_e32 v34, v59, v34
	v_add_f32_e32 v32, v32, v34
	v_add_f32_e32 v32, v33, v32
	ds_bpermute_b32 v33, v217, v32
	s_waitcnt lgkmcnt(0)
	v_add_f32_e32 v32, v32, v33
	ds_bpermute_b32 v33, v218, v32
	s_waitcnt lgkmcnt(0)
	v_add_f32_e32 v32, v32, v33
	ds_bpermute_b32 v33, v219, v32
	s_waitcnt lgkmcnt(0)
	v_add_f32_e32 v32, v32, v33
	ds_bpermute_b32 v33, v220, v32
	s_waitcnt lgkmcnt(0)
	v_add_f32_e32 v32, v32, v33
	ds_bpermute_b32 v33, v215, v32
	s_waitcnt lgkmcnt(0)
	v_add_f32_e32 v32, v32, v33
	ds_bpermute_b32 v33, v216, v32
	s_waitcnt lgkmcnt(0)
	v_add_f32_e32 v32, v32, v33
	v_fmamk_f32 v32, v32, 0x3a800000, v227
	v_mul_f32_e32 v33, 0x4f800000, v32
	v_cmp_gt_f32_e32 vcc, s45, v32
	s_nop 1
	v_cndmask_b32_e32 v32, v32, v33, vcc
	v_sqrt_f32_e32 v33, v32
	s_nop 0
	v_add_u32_e32 v34, -1, v33
	v_add_u32_e32 v35, 1, v33
	v_fma_f32 v48, -v34, v33, v32
	v_fma_f32 v49, -v35, v33, v32
	v_cmp_ge_f32_e64 s[10:11], 0, v48
	s_nop 1
	v_cndmask_b32_e64 v33, v33, v34, s[10:11]
	v_cmp_lt_f32_e64 s[10:11], 0, v49
	v_lshl_add_u64 v[48:49], v[80:81], 0, s[34:35]
	s_nop 0
	v_cndmask_b32_e64 v33, v33, v35, s[10:11]
	v_mul_f32_e32 v34, 0x37800000, v33
	v_cndmask_b32_e32 v33, v33, v34, vcc
	v_cmp_class_f32_e32 vcc, v32, v228
	s_nop 1
	v_cndmask_b32_e32 v32, v33, v32, vcc
	v_div_scale_f32 v33, s[10:11], v32, v32, 1.0
	v_rcp_f32_e32 v34, v33
	v_div_scale_f32 v35, vcc, 1.0, v32, 1.0
	v_fma_f32 v50, -v33, v34, 1.0
	v_fmac_f32_e32 v34, v50, v34
	v_mul_f32_e32 v50, v35, v34
	v_fma_f32 v51, -v33, v50, v35
	v_fmac_f32_e32 v50, v51, v34
	v_fma_f32 v33, -v33, v50, v35
	v_div_fmas_f32 v33, v33, v34, v50
	v_div_fixup_f32 v50, v33, v32, 1.0
	v_pk_mul_f32 v[10:11], v[10:11], v[50:51] op_sel_hi:[1,0]
	v_pk_mul_f32 v[14:15], v[14:15], v[50:51] op_sel_hi:[1,0]
	s_waitcnt vmcnt(0)
	v_pk_mul_f32 v[32:33], v[120:121], v[10:11]
	v_pk_mul_f32 v[34:35], v[122:123], v[14:15]
	global_store_dwordx4 v[48:49], v[32:35], off
	s_nop 1
	v_mov_b64_e32 v[32:33], v[168:169]
	v_mov_b64_e32 v[34:35], v[170:171]
	v_pk_mul_f32 v[10:11], v[46:47], v[50:51] op_sel_hi:[1,0]
	v_pk_mul_f32 v[14:15], v[44:45], v[50:51] op_sel_hi:[1,0]
	s_nop 0
	v_pk_mul_f32 v[34:35], v[34:35], v[10:11]
	v_pk_mul_f32 v[32:33], v[32:33], v[14:15]
	global_store_dwordx4 v[48:49], v[32:35], off offset:16
	s_nop 1
	v_mov_b64_e32 v[32:33], v[172:173]
	v_mov_b64_e32 v[34:35], v[174:175]
	v_pk_mul_f32 v[10:11], v[38:39], v[50:51] op_sel_hi:[1,0]
	v_pk_mul_f32 v[14:15], v[36:37], v[50:51] op_sel_hi:[1,0]
	s_nop 0
	v_pk_mul_f32 v[34:35], v[34:35], v[10:11]
	v_pk_mul_f32 v[32:33], v[32:33], v[14:15]
	global_store_dwordx4 v[48:49], v[32:35], off offset:32
	s_nop 1
	v_mov_b64_e32 v[32:33], v[176:177]
	v_mov_b64_e32 v[34:35], v[178:179]
	v_pk_mul_f32 v[10:11], v[42:43], v[50:51] op_sel_hi:[1,0]
	v_pk_mul_f32 v[14:15], v[40:41], v[50:51] op_sel_hi:[1,0]
	s_nop 0
	v_pk_mul_f32 v[34:35], v[34:35], v[10:11]
	v_pk_mul_f32 v[32:33], v[32:33], v[14:15]
	global_store_dwordx4 v[48:49], v[32:35], off offset:48
	s_and_b64 vcc, exec, s[8:9]
	s_mov_b64 s[10:11], -1
	s_cbranch_vccz .LBB0_1765
